# v42 + drop pre-barrier lgkmcnt(0) in K-loops (post-barrier wait before the MFMAs remains)
# speedup vs baseline: 1.0254x; 1.0021x over previous
.LBB0_261:
	s_add_u32 s0, s76, 0xfff80080
	s_addc_u32 s1, s77, -1
	s_and_b64 s[84:85], s[84:85], exec
	s_cselect_b32 vcc_hi, s22, s1
	s_cselect_b32 vcc_lo, s23, s0
	s_cselect_b32 s85, s49, s58
	s_cselect_b32 s84, s57, s51
	s_add_i32 s0, 0, 0x10000
	s_add_i32 s1, 0, 0x14000
	v_add_u32_e32 v158, s0, v176
	v_add_u32_e32 v174, s1, v176
	ds_read_b128 v[146:149], v158
	ds_read_b128 v[150:153], v158 offset:1024
	ds_read_b128 v[154:157], v158 offset:2048
	ds_read_b128 v[158:161], v158 offset:3072
	ds_read_b128 v[162:165], v174
	ds_read_b128 v[166:169], v174 offset:1024
	ds_read_b128 v[170:173], v174 offset:2048
	ds_read_b128 v[178:181], v174 offset:3072
	s_add_i32 m0, s21, 0xc000
	ds_read_b128 v[182:185], v177
	ds_read_b128 v[186:189], v177 offset:1024
	ds_read_b128 v[190:193], v177 offset:2048
	ds_read_b128 v[204:207], v177 offset:3072
	ds_read_b128 v[208:211], v177 offset:4096
	ds_read_b128 v[212:215], v177 offset:5120
	ds_read_b128 v[216:219], v177 offset:6144
	ds_read_b128 v[220:223], v177 offset:7168
	global_load_lds_dwordx4 v138, s[76:77]
	s_add_i32 m0, s21, 0xe000
	s_nop 0
	global_load_lds_dwordx4 v140, s[76:77]
	s_waitcnt vmcnt(8)
	s_barrier
	s_setprio 1
	s_waitcnt lgkmcnt(0)
	v_mfma_f32_16x16x32_bf16 v[126:129], v[146:149], v[182:185], v[126:129]
	v_mfma_f32_16x16x32_bf16 v[126:129], v[150:153], v[186:189], v[126:129]
	v_mfma_f32_16x16x32_bf16 v[122:125], v[158:161], v[186:189], v[122:125]
	v_mfma_f32_16x16x32_bf16 v[122:125], v[154:157], v[182:185], v[122:125]
	v_mfma_f32_16x16x32_bf16 v[118:121], v[162:165], v[182:185], v[118:121]
	v_mfma_f32_16x16x32_bf16 v[118:121], v[166:169], v[186:189], v[118:121]
	v_mfma_f32_16x16x32_bf16 v[114:117], v[178:181], v[186:189], v[114:117]
	v_mfma_f32_16x16x32_bf16 v[114:117], v[170:173], v[182:185], v[114:117]
	v_mfma_f32_16x16x32_bf16 v[98:101], v[170:173], v[190:193], v[98:101]
	v_mfma_f32_16x16x32_bf16 v[98:101], v[178:181], v[204:207], v[98:101]
	v_mfma_f32_16x16x32_bf16 v[102:105], v[166:169], v[204:207], v[102:105]
	v_mfma_f32_16x16x32_bf16 v[102:105], v[162:165], v[190:193], v[102:105]
	v_mfma_f32_16x16x32_bf16 v[106:109], v[154:157], v[190:193], v[106:109]
	v_mfma_f32_16x16x32_bf16 v[106:109], v[158:161], v[204:207], v[106:109]
	v_mfma_f32_16x16x32_bf16 v[110:113], v[150:153], v[204:207], v[110:113]
	v_mfma_f32_16x16x32_bf16 v[110:113], v[146:149], v[190:193], v[110:113]
	v_mfma_f32_16x16x32_bf16 v[94:97], v[146:149], v[208:211], v[94:97]
	v_mfma_f32_16x16x32_bf16 v[94:97], v[150:153], v[212:215], v[94:97]
	v_mfma_f32_16x16x32_bf16 v[90:93], v[158:161], v[212:215], v[90:93]
	v_mfma_f32_16x16x32_bf16 v[90:93], v[154:157], v[208:211], v[90:93]
	v_mfma_f32_16x16x32_bf16 v[86:89], v[162:165], v[208:211], v[86:89]
	v_mfma_f32_16x16x32_bf16 v[86:89], v[166:169], v[212:215], v[86:89]
	v_mfma_f32_16x16x32_bf16 v[82:85], v[178:181], v[212:215], v[82:85]
	v_mfma_f32_16x16x32_bf16 v[82:85], v[170:173], v[208:211], v[82:85]
	v_mfma_f32_16x16x32_bf16 v[66:69], v[170:173], v[216:219], v[66:69]
	v_mfma_f32_16x16x32_bf16 v[66:69], v[178:181], v[220:223], v[66:69]
	v_mfma_f32_16x16x32_bf16 v[70:73], v[166:169], v[220:223], v[70:73]
	v_mfma_f32_16x16x32_bf16 v[70:73], v[162:165], v[216:219], v[70:73]
	v_mfma_f32_16x16x32_bf16 v[74:77], v[154:157], v[216:219], v[74:77]
	v_mfma_f32_16x16x32_bf16 v[74:77], v[158:161], v[220:223], v[74:77]
	v_mfma_f32_16x16x32_bf16 v[78:81], v[150:153], v[220:223], v[78:81]
	v_mfma_f32_16x16x32_bf16 v[78:81], v[146:149], v[216:219], v[78:81]
	s_setprio 0
	s_barrier
	s_add_i32 s0, s0, s20
	s_mov_b32 m0, s0
	ds_read_b128 v[182:185], v177 offset:16384
	ds_read_b128 v[186:189], v177 offset:17408
	ds_read_b128 v[190:193], v177 offset:18432
	ds_read_b128 v[204:207], v177 offset:19456
	ds_read_b128 v[208:211], v177 offset:20480
	ds_read_b128 v[212:215], v177 offset:21504
	ds_read_b128 v[216:219], v177 offset:22528
	ds_read_b128 v[220:223], v177 offset:23552
	global_load_lds_dwordx4 v132, s[84:85]
	s_add_i32 m0, s0, 0x2000
	s_add_u32 s94, s84, 0x80000
	s_addc_u32 s95, s85, 0
	s_add_i32 s0, s1, s20
	global_load_lds_dwordx4 v130, s[84:85]
	s_mov_b32 m0, s0
	s_nop 0
	global_load_lds_dwordx4 v132, s[94:95]
	s_add_i32 m0, s0, 0x2000
	s_nop 0
	global_load_lds_dwordx4 v130, s[94:95]
	s_mov_b32 m0, s21
	s_nop 0
	global_load_lds_dwordx4 v132, vcc
	s_mov_b32 m0, s26
	s_nop 0
	global_load_lds_dwordx4 v130, vcc
	s_waitcnt vmcnt(8)
	s_barrier
	s_setprio 1
	s_waitcnt lgkmcnt(0)
	v_mfma_f32_16x16x32_bf16 v[62:65], v[146:149], v[182:185], v[62:65]
	v_mfma_f32_16x16x32_bf16 v[62:65], v[150:153], v[186:189], v[62:65]
	v_mfma_f32_16x16x32_bf16 v[58:61], v[158:161], v[186:189], v[58:61]
	v_mfma_f32_16x16x32_bf16 v[58:61], v[154:157], v[182:185], v[58:61]
	v_mfma_f32_16x16x32_bf16 v[54:57], v[162:165], v[182:185], v[54:57]
	v_mfma_f32_16x16x32_bf16 v[54:57], v[166:169], v[186:189], v[54:57]
	v_mfma_f32_16x16x32_bf16 v[50:53], v[178:181], v[186:189], v[50:53]
	v_mfma_f32_16x16x32_bf16 v[50:53], v[170:173], v[182:185], v[50:53]
	v_mfma_f32_16x16x32_bf16 v[34:37], v[170:173], v[190:193], v[34:37]
	v_mfma_f32_16x16x32_bf16 v[34:37], v[178:181], v[204:207], v[34:37]
	v_mfma_f32_16x16x32_bf16 v[38:41], v[166:169], v[204:207], v[38:41]
	v_mfma_f32_16x16x32_bf16 v[38:41], v[162:165], v[190:193], v[38:41]
	v_mfma_f32_16x16x32_bf16 v[42:45], v[154:157], v[190:193], v[42:45]
	v_mfma_f32_16x16x32_bf16 v[42:45], v[158:161], v[204:207], v[42:45]
	v_mfma_f32_16x16x32_bf16 v[46:49], v[150:153], v[204:207], v[46:49]
	v_mfma_f32_16x16x32_bf16 v[46:49], v[146:149], v[190:193], v[46:49]
	v_mfma_f32_16x16x32_bf16 v[30:33], v[146:149], v[208:211], v[30:33]
	v_mfma_f32_16x16x32_bf16 v[30:33], v[150:153], v[212:215], v[30:33]
	v_mfma_f32_16x16x32_bf16 v[26:29], v[158:161], v[212:215], v[26:29]
	v_mfma_f32_16x16x32_bf16 v[26:29], v[154:157], v[208:211], v[26:29]
	v_mfma_f32_16x16x32_bf16 v[22:25], v[162:165], v[208:211], v[22:25]
	v_mfma_f32_16x16x32_bf16 v[22:25], v[166:169], v[212:215], v[22:25]
	v_mfma_f32_16x16x32_bf16 v[18:21], v[178:181], v[212:215], v[18:21]
	v_mfma_f32_16x16x32_bf16 v[18:21], v[170:173], v[208:211], v[18:21]
	v_mfma_f32_16x16x32_bf16 v[2:5], v[170:173], v[216:219], v[2:5]
	v_mfma_f32_16x16x32_bf16 v[2:5], v[178:181], v[220:223], v[2:5]
	v_mfma_f32_16x16x32_bf16 v[6:9], v[166:169], v[220:223], v[6:9]
	v_mfma_f32_16x16x32_bf16 v[6:9], v[162:165], v[216:219], v[6:9]
	v_mfma_f32_16x16x32_bf16 v[10:13], v[154:157], v[216:219], v[10:13]
	v_mfma_f32_16x16x32_bf16 v[10:13], v[158:161], v[220:223], v[10:13]
	v_mfma_f32_16x16x32_bf16 v[14:17], v[150:153], v[220:223], v[14:17]
	v_mfma_f32_16x16x32_bf16 v[14:17], v[146:149], v[216:219], v[14:17]
	s_setprio 0
	s_barrier
	s_add_i32 s0, 0, 0x18000
	s_add_i32 s1, 0, 0x1c000
	v_add_u32_e32 v158, s0, v176
	v_add_u32_e32 v178, s1, v176
	ds_read_b128 v[146:149], v158
	ds_read_b128 v[150:153], v158 offset:1024
	ds_read_b128 v[154:157], v158 offset:2048
	ds_read_b128 v[158:161], v158 offset:3072
	ds_read_b128 v[162:165], v178
	ds_read_b128 v[166:169], v178 offset:1024
	ds_read_b128 v[170:173], v178 offset:2048
	ds_read_b128 v[178:181], v178 offset:3072
	s_add_u32 s94, vcc_lo, 0x80000
	s_addc_u32 s95, vcc_hi, 0
	s_mov_b32 m0, s27
	ds_read_b128 v[182:185], v177 offset:32768
	ds_read_b128 v[186:189], v177 offset:33792
	ds_read_b128 v[190:193], v177 offset:34816
	ds_read_b128 v[204:207], v177 offset:35840
	ds_read_b128 v[208:211], v177 offset:36864
	ds_read_b128 v[212:215], v177 offset:37888
	ds_read_b128 v[216:219], v177 offset:38912
	ds_read_b128 v[220:223], v177 offset:39936
	global_load_lds_dwordx4 v132, s[94:95]
	s_mov_b32 m0, s29
	s_nop 0
	global_load_lds_dwordx4 v130, s[94:95]
	s_waitcnt vmcnt(8)
	s_barrier
	s_setprio 1
	s_waitcnt lgkmcnt(0)
	v_mfma_f32_16x16x32_bf16 v[126:129], v[146:149], v[182:185], v[126:129]
	v_mfma_f32_16x16x32_bf16 v[126:129], v[150:153], v[186:189], v[126:129]
	v_mfma_f32_16x16x32_bf16 v[122:125], v[158:161], v[186:189], v[122:125]
	v_mfma_f32_16x16x32_bf16 v[122:125], v[154:157], v[182:185], v[122:125]
	v_mfma_f32_16x16x32_bf16 v[118:121], v[162:165], v[182:185], v[118:121]
	v_mfma_f32_16x16x32_bf16 v[118:121], v[166:169], v[186:189], v[118:121]
	v_mfma_f32_16x16x32_bf16 v[114:117], v[178:181], v[186:189], v[114:117]
	v_mfma_f32_16x16x32_bf16 v[114:117], v[170:173], v[182:185], v[114:117]
	v_mfma_f32_16x16x32_bf16 v[98:101], v[170:173], v[190:193], v[98:101]
	v_mfma_f32_16x16x32_bf16 v[98:101], v[178:181], v[204:207], v[98:101]
	v_mfma_f32_16x16x32_bf16 v[102:105], v[166:169], v[204:207], v[102:105]
	v_mfma_f32_16x16x32_bf16 v[102:105], v[162:165], v[190:193], v[102:105]
	v_mfma_f32_16x16x32_bf16 v[106:109], v[154:157], v[190:193], v[106:109]
	v_mfma_f32_16x16x32_bf16 v[106:109], v[158:161], v[204:207], v[106:109]
	v_mfma_f32_16x16x32_bf16 v[110:113], v[150:153], v[204:207], v[110:113]
	v_mfma_f32_16x16x32_bf16 v[110:113], v[146:149], v[190:193], v[110:113]
	v_mfma_f32_16x16x32_bf16 v[94:97], v[146:149], v[208:211], v[94:97]
	v_mfma_f32_16x16x32_bf16 v[94:97], v[150:153], v[212:215], v[94:97]
	v_mfma_f32_16x16x32_bf16 v[90:93], v[158:161], v[212:215], v[90:93]
	v_mfma_f32_16x16x32_bf16 v[90:93], v[154:157], v[208:211], v[90:93]
	v_mfma_f32_16x16x32_bf16 v[86:89], v[162:165], v[208:211], v[86:89]
	v_mfma_f32_16x16x32_bf16 v[86:89], v[166:169], v[212:215], v[86:89]
	v_mfma_f32_16x16x32_bf16 v[82:85], v[178:181], v[212:215], v[82:85]
	v_mfma_f32_16x16x32_bf16 v[82:85], v[170:173], v[208:211], v[82:85]
	v_mfma_f32_16x16x32_bf16 v[66:69], v[170:173], v[216:219], v[66:69]
	v_mfma_f32_16x16x32_bf16 v[66:69], v[178:181], v[220:223], v[66:69]
	v_mfma_f32_16x16x32_bf16 v[70:73], v[166:169], v[220:223], v[70:73]
	v_mfma_f32_16x16x32_bf16 v[70:73], v[162:165], v[216:219], v[70:73]
	v_mfma_f32_16x16x32_bf16 v[74:77], v[154:157], v[216:219], v[74:77]
	v_mfma_f32_16x16x32_bf16 v[74:77], v[158:161], v[220:223], v[74:77]
	v_mfma_f32_16x16x32_bf16 v[78:81], v[150:153], v[220:223], v[78:81]
	v_mfma_f32_16x16x32_bf16 v[78:81], v[146:149], v[216:219], v[78:81]
	s_setprio 0
	s_barrier
	s_add_u32 s98, s84, 0x80
	s_addc_u32 s99, s85, 0
	s_add_u32 s100, vcc_lo, 0x80
	s_addc_u32 s101, vcc_hi, 0
	s_add_i32 s0, s0, s20
	s_mov_b32 m0, s0
	ds_read_b128 v[182:185], v177 offset:49152
	ds_read_b128 v[186:189], v177 offset:50176
	ds_read_b128 v[190:193], v177 offset:51200
	ds_read_b128 v[204:207], v177 offset:52224
	ds_read_b128 v[208:211], v177 offset:53248
	ds_read_b128 v[212:215], v177 offset:54272
	ds_read_b128 v[216:219], v177 offset:55296
	ds_read_b128 v[220:223], v177 offset:56320
	global_load_lds_dwordx4 v132, s[98:99]
	s_add_i32 m0, s0, 0x2000
	s_add_u32 s84, s84, 0x80080
	s_addc_u32 s85, s85, 0
	s_add_i32 s0, s1, s20
	global_load_lds_dwordx4 v130, s[98:99]
	s_mov_b32 m0, s0
	s_nop 0
	global_load_lds_dwordx4 v132, s[84:85]
	s_add_i32 m0, s0, 0x2000
	s_nop 0
	global_load_lds_dwordx4 v130, s[84:85]
	s_mov_b32 m0, s40
	s_nop 0
	global_load_lds_dwordx4 v132, s[100:101]
	s_mov_b32 m0, s41
	s_nop 0
	global_load_lds_dwordx4 v130, s[100:101]
	s_waitcnt vmcnt(8)
	s_barrier
	s_setprio 1
	s_waitcnt lgkmcnt(0)
	v_mfma_f32_16x16x32_bf16 v[62:65], v[146:149], v[182:185], v[62:65]
	v_mfma_f32_16x16x32_bf16 v[62:65], v[150:153], v[186:189], v[62:65]
	v_mfma_f32_16x16x32_bf16 v[58:61], v[158:161], v[186:189], v[58:61]
	v_mfma_f32_16x16x32_bf16 v[58:61], v[154:157], v[182:185], v[58:61]
	v_mfma_f32_16x16x32_bf16 v[54:57], v[162:165], v[182:185], v[54:57]
	v_mfma_f32_16x16x32_bf16 v[54:57], v[166:169], v[186:189], v[54:57]
	v_mfma_f32_16x16x32_bf16 v[50:53], v[178:181], v[186:189], v[50:53]
	v_mfma_f32_16x16x32_bf16 v[50:53], v[170:173], v[182:185], v[50:53]
	v_mfma_f32_16x16x32_bf16 v[34:37], v[170:173], v[190:193], v[34:37]
	v_mfma_f32_16x16x32_bf16 v[34:37], v[178:181], v[204:207], v[34:37]
	v_mfma_f32_16x16x32_bf16 v[38:41], v[166:169], v[204:207], v[38:41]
	v_mfma_f32_16x16x32_bf16 v[38:41], v[162:165], v[190:193], v[38:41]
	v_mfma_f32_16x16x32_bf16 v[42:45], v[154:157], v[190:193], v[42:45]
	v_mfma_f32_16x16x32_bf16 v[42:45], v[158:161], v[204:207], v[42:45]
	v_mfma_f32_16x16x32_bf16 v[46:49], v[150:153], v[204:207], v[46:49]
	v_mfma_f32_16x16x32_bf16 v[46:49], v[146:149], v[190:193], v[46:49]
	v_mfma_f32_16x16x32_bf16 v[30:33], v[146:149], v[208:211], v[30:33]
	v_mfma_f32_16x16x32_bf16 v[30:33], v[150:153], v[212:215], v[30:33]
	v_mfma_f32_16x16x32_bf16 v[26:29], v[158:161], v[212:215], v[26:29]
	v_mfma_f32_16x16x32_bf16 v[26:29], v[154:157], v[208:211], v[26:29]
	v_mfma_f32_16x16x32_bf16 v[22:25], v[162:165], v[208:211], v[22:25]
	v_mfma_f32_16x16x32_bf16 v[22:25], v[166:169], v[212:215], v[22:25]
	v_mfma_f32_16x16x32_bf16 v[18:21], v[178:181], v[212:215], v[18:21]
	v_mfma_f32_16x16x32_bf16 v[18:21], v[170:173], v[208:211], v[18:21]
	v_mfma_f32_16x16x32_bf16 v[2:5], v[170:173], v[216:219], v[2:5]
	v_mfma_f32_16x16x32_bf16 v[2:5], v[178:181], v[220:223], v[2:5]
	v_mfma_f32_16x16x32_bf16 v[6:9], v[166:169], v[220:223], v[6:9]
	v_mfma_f32_16x16x32_bf16 v[6:9], v[162:165], v[216:219], v[6:9]
	v_mfma_f32_16x16x32_bf16 v[10:13], v[154:157], v[216:219], v[10:13]
	v_mfma_f32_16x16x32_bf16 v[10:13], v[158:161], v[220:223], v[10:13]
	v_mfma_f32_16x16x32_bf16 v[14:17], v[150:153], v[220:223], v[14:17]
	v_mfma_f32_16x16x32_bf16 v[14:17], v[146:149], v[216:219], v[14:17]
	s_setprio 0
	s_barrier
	s_add_i32 s65, s65, 2
	s_add_u32 s76, s76, 0x100
	s_addc_u32 s77, s77, 0
	s_add_u32 s51, s51, 0x100
	s_addc_u32 s58, s58, 0
	s_cmp_gt_u32 s65, 29
	s_cbranch_scc1 .LBB0_264

.LBB0_285:
	s_add_u32 s0, s76, 0xfff80080
	s_addc_u32 s1, s77, -1
	s_and_b64 s[70:71], s[70:71], exec
	s_cselect_b32 vcc_hi, s21, s1
	s_cselect_b32 vcc_lo, s22, s0
	s_cselect_b32 s71, s23, s41
	s_cselect_b32 s70, s39, s7
	s_add_i32 s0, 0, 0x10000
	s_add_i32 s1, 0, 0x14000
	v_add_u32_e32 v146, s0, v1
	v_add_u32_e32 v174, s1, v1
	ds_read_b128 v[134:137], v146
	ds_read_b128 v[138:141], v146 offset:1024
	ds_read_b128 v[142:145], v146 offset:2048
	ds_read_b128 v[146:149], v146 offset:3072
	ds_read_b128 v[150:153], v174
	ds_read_b128 v[154:157], v174 offset:1024
	ds_read_b128 v[158:161], v174 offset:2048
	ds_read_b128 v[174:177], v174 offset:3072
	s_add_i32 m0, s67, 0xc000
	ds_read_b128 v[178:181], v222
	ds_read_b128 v[182:185], v222 offset:1024
	ds_read_b128 v[186:189], v222 offset:2048
	ds_read_b128 v[190:193], v222 offset:3072
	ds_read_b128 v[204:207], v222 offset:4096
	ds_read_b128 v[208:211], v222 offset:5120
	ds_read_b128 v[212:215], v222 offset:6144
	ds_read_b128 v[216:219], v222 offset:7168
	global_load_lds_dwordx4 v170, s[76:77]
	s_add_i32 m0, s67, 0xe000
	s_nop 0
	global_load_lds_dwordx4 v172, s[76:77]
	s_waitcnt vmcnt(8)
	s_barrier
	s_setprio 1
	s_waitcnt lgkmcnt(0)
	v_mfma_f32_16x16x32_bf16 v[126:129], v[134:137], v[178:181], v[126:129]
	v_mfma_f32_16x16x32_bf16 v[126:129], v[138:141], v[182:185], v[126:129]
	v_mfma_f32_16x16x32_bf16 v[122:125], v[146:149], v[182:185], v[122:125]
	v_mfma_f32_16x16x32_bf16 v[122:125], v[142:145], v[178:181], v[122:125]
	v_mfma_f32_16x16x32_bf16 v[118:121], v[150:153], v[178:181], v[118:121]
	v_mfma_f32_16x16x32_bf16 v[118:121], v[154:157], v[182:185], v[118:121]
	v_mfma_f32_16x16x32_bf16 v[114:117], v[174:177], v[182:185], v[114:117]
	v_mfma_f32_16x16x32_bf16 v[114:117], v[158:161], v[178:181], v[114:117]
	v_mfma_f32_16x16x32_bf16 v[98:101], v[158:161], v[186:189], v[98:101]
	v_mfma_f32_16x16x32_bf16 v[98:101], v[174:177], v[190:193], v[98:101]
	v_mfma_f32_16x16x32_bf16 v[102:105], v[154:157], v[190:193], v[102:105]
	v_mfma_f32_16x16x32_bf16 v[102:105], v[150:153], v[186:189], v[102:105]
	v_mfma_f32_16x16x32_bf16 v[106:109], v[142:145], v[186:189], v[106:109]
	v_mfma_f32_16x16x32_bf16 v[106:109], v[146:149], v[190:193], v[106:109]
	v_mfma_f32_16x16x32_bf16 v[110:113], v[138:141], v[190:193], v[110:113]
	v_mfma_f32_16x16x32_bf16 v[110:113], v[134:137], v[186:189], v[110:113]
	v_mfma_f32_16x16x32_bf16 v[94:97], v[134:137], v[204:207], v[94:97]
	v_mfma_f32_16x16x32_bf16 v[94:97], v[138:141], v[208:211], v[94:97]
	v_mfma_f32_16x16x32_bf16 v[90:93], v[146:149], v[208:211], v[90:93]
	v_mfma_f32_16x16x32_bf16 v[90:93], v[142:145], v[204:207], v[90:93]
	v_mfma_f32_16x16x32_bf16 v[86:89], v[150:153], v[204:207], v[86:89]
	v_mfma_f32_16x16x32_bf16 v[86:89], v[154:157], v[208:211], v[86:89]
	v_mfma_f32_16x16x32_bf16 v[82:85], v[174:177], v[208:211], v[82:85]
	v_mfma_f32_16x16x32_bf16 v[82:85], v[158:161], v[204:207], v[82:85]
	v_mfma_f32_16x16x32_bf16 v[66:69], v[158:161], v[212:215], v[66:69]
	v_mfma_f32_16x16x32_bf16 v[66:69], v[174:177], v[216:219], v[66:69]
	v_mfma_f32_16x16x32_bf16 v[70:73], v[154:157], v[216:219], v[70:73]
	v_mfma_f32_16x16x32_bf16 v[70:73], v[150:153], v[212:215], v[70:73]
	v_mfma_f32_16x16x32_bf16 v[74:77], v[142:145], v[212:215], v[74:77]
	v_mfma_f32_16x16x32_bf16 v[74:77], v[146:149], v[216:219], v[74:77]
	v_mfma_f32_16x16x32_bf16 v[78:81], v[138:141], v[216:219], v[78:81]
	v_mfma_f32_16x16x32_bf16 v[78:81], v[134:137], v[212:215], v[78:81]
	s_setprio 0
	s_barrier
	s_add_i32 s0, s0, s54
	s_mov_b32 m0, s0
	ds_read_b128 v[178:181], v222 offset:16384
	ds_read_b128 v[182:185], v222 offset:17408
	ds_read_b128 v[186:189], v222 offset:18432
	ds_read_b128 v[190:193], v222 offset:19456
	ds_read_b128 v[204:207], v222 offset:20480
	ds_read_b128 v[208:211], v222 offset:21504
	ds_read_b128 v[212:215], v222 offset:22528
	ds_read_b128 v[216:219], v222 offset:23552
	global_load_lds_dwordx4 v164, s[70:71]
	s_add_i32 m0, s0, 0x2000
	s_add_u32 s44, s70, 0x80000
	s_addc_u32 s45, s71, 0
	s_add_i32 s0, s1, s54
	global_load_lds_dwordx4 v162, s[70:71]
	s_mov_b32 m0, s0
	s_nop 0
	global_load_lds_dwordx4 v164, s[44:45]
	s_add_i32 m0, s0, 0x2000
	s_nop 0
	global_load_lds_dwordx4 v162, s[44:45]
	s_mov_b32 m0, s67
	s_nop 0
	global_load_lds_dwordx4 v164, vcc
	s_mov_b32 m0, s68
	s_nop 0
	global_load_lds_dwordx4 v162, vcc
	s_waitcnt vmcnt(8)
	s_barrier
	s_setprio 1
	s_waitcnt lgkmcnt(0)
	v_mfma_f32_16x16x32_bf16 v[62:65], v[134:137], v[178:181], v[62:65]
	v_mfma_f32_16x16x32_bf16 v[62:65], v[138:141], v[182:185], v[62:65]
	v_mfma_f32_16x16x32_bf16 v[58:61], v[146:149], v[182:185], v[58:61]
	v_mfma_f32_16x16x32_bf16 v[58:61], v[142:145], v[178:181], v[58:61]
	v_mfma_f32_16x16x32_bf16 v[54:57], v[150:153], v[178:181], v[54:57]
	v_mfma_f32_16x16x32_bf16 v[54:57], v[154:157], v[182:185], v[54:57]
	v_mfma_f32_16x16x32_bf16 v[50:53], v[174:177], v[182:185], v[50:53]
	v_mfma_f32_16x16x32_bf16 v[50:53], v[158:161], v[178:181], v[50:53]
	v_mfma_f32_16x16x32_bf16 v[34:37], v[158:161], v[186:189], v[34:37]
	v_mfma_f32_16x16x32_bf16 v[34:37], v[174:177], v[190:193], v[34:37]
	v_mfma_f32_16x16x32_bf16 v[38:41], v[154:157], v[190:193], v[38:41]
	v_mfma_f32_16x16x32_bf16 v[38:41], v[150:153], v[186:189], v[38:41]
	v_mfma_f32_16x16x32_bf16 v[42:45], v[142:145], v[186:189], v[42:45]
	v_mfma_f32_16x16x32_bf16 v[42:45], v[146:149], v[190:193], v[42:45]
	v_mfma_f32_16x16x32_bf16 v[46:49], v[138:141], v[190:193], v[46:49]
	v_mfma_f32_16x16x32_bf16 v[46:49], v[134:137], v[186:189], v[46:49]
	v_mfma_f32_16x16x32_bf16 v[30:33], v[134:137], v[204:207], v[30:33]
	v_mfma_f32_16x16x32_bf16 v[30:33], v[138:141], v[208:211], v[30:33]
	v_mfma_f32_16x16x32_bf16 v[26:29], v[146:149], v[208:211], v[26:29]
	v_mfma_f32_16x16x32_bf16 v[26:29], v[142:145], v[204:207], v[26:29]
	v_mfma_f32_16x16x32_bf16 v[22:25], v[150:153], v[204:207], v[22:25]
	v_mfma_f32_16x16x32_bf16 v[22:25], v[154:157], v[208:211], v[22:25]
	v_mfma_f32_16x16x32_bf16 v[18:21], v[174:177], v[208:211], v[18:21]
	v_mfma_f32_16x16x32_bf16 v[18:21], v[158:161], v[204:207], v[18:21]
	v_mfma_f32_16x16x32_bf16 v[2:5], v[158:161], v[212:215], v[2:5]
	v_mfma_f32_16x16x32_bf16 v[2:5], v[174:177], v[216:219], v[2:5]
	v_mfma_f32_16x16x32_bf16 v[6:9], v[154:157], v[216:219], v[6:9]
	v_mfma_f32_16x16x32_bf16 v[6:9], v[150:153], v[212:215], v[6:9]
	v_mfma_f32_16x16x32_bf16 v[10:13], v[142:145], v[212:215], v[10:13]
	v_mfma_f32_16x16x32_bf16 v[10:13], v[146:149], v[216:219], v[10:13]
	v_mfma_f32_16x16x32_bf16 v[14:17], v[138:141], v[216:219], v[14:17]
	v_mfma_f32_16x16x32_bf16 v[14:17], v[134:137], v[212:215], v[14:17]
	s_setprio 0
	s_barrier
	s_add_i32 s0, 0, 0x18000
	s_add_i32 s1, 0, 0x1c000
	v_add_u32_e32 v146, s0, v1
	v_add_u32_e32 v174, s1, v1
	ds_read_b128 v[134:137], v146
	ds_read_b128 v[138:141], v146 offset:1024
	ds_read_b128 v[142:145], v146 offset:2048
	ds_read_b128 v[146:149], v146 offset:3072
	ds_read_b128 v[150:153], v174
	ds_read_b128 v[154:157], v174 offset:1024
	ds_read_b128 v[158:161], v174 offset:2048
	ds_read_b128 v[174:177], v174 offset:3072
	s_add_u32 s44, vcc_lo, 0x80000
	s_addc_u32 s45, vcc_hi, 0
	s_mov_b32 m0, s8
	ds_read_b128 v[178:181], v222 offset:32768
	ds_read_b128 v[182:185], v222 offset:33792
	ds_read_b128 v[186:189], v222 offset:34816
	ds_read_b128 v[190:193], v222 offset:35840
	ds_read_b128 v[204:207], v222 offset:36864
	ds_read_b128 v[208:211], v222 offset:37888
	ds_read_b128 v[212:215], v222 offset:38912
	ds_read_b128 v[216:219], v222 offset:39936
	global_load_lds_dwordx4 v164, s[44:45]
	s_mov_b32 m0, s9
	s_nop 0
	global_load_lds_dwordx4 v162, s[44:45]
	s_waitcnt vmcnt(8)
	s_barrier
	s_setprio 1
	s_waitcnt lgkmcnt(0)
	v_mfma_f32_16x16x32_bf16 v[126:129], v[134:137], v[178:181], v[126:129]
	v_mfma_f32_16x16x32_bf16 v[126:129], v[138:141], v[182:185], v[126:129]
	v_mfma_f32_16x16x32_bf16 v[122:125], v[146:149], v[182:185], v[122:125]
	v_mfma_f32_16x16x32_bf16 v[122:125], v[142:145], v[178:181], v[122:125]
	v_mfma_f32_16x16x32_bf16 v[118:121], v[150:153], v[178:181], v[118:121]
	v_mfma_f32_16x16x32_bf16 v[118:121], v[154:157], v[182:185], v[118:121]
	v_mfma_f32_16x16x32_bf16 v[114:117], v[174:177], v[182:185], v[114:117]
	v_mfma_f32_16x16x32_bf16 v[114:117], v[158:161], v[178:181], v[114:117]
	v_mfma_f32_16x16x32_bf16 v[98:101], v[158:161], v[186:189], v[98:101]
	v_mfma_f32_16x16x32_bf16 v[98:101], v[174:177], v[190:193], v[98:101]
	v_mfma_f32_16x16x32_bf16 v[102:105], v[154:157], v[190:193], v[102:105]
	v_mfma_f32_16x16x32_bf16 v[102:105], v[150:153], v[186:189], v[102:105]
	v_mfma_f32_16x16x32_bf16 v[106:109], v[142:145], v[186:189], v[106:109]
	v_mfma_f32_16x16x32_bf16 v[106:109], v[146:149], v[190:193], v[106:109]
	v_mfma_f32_16x16x32_bf16 v[110:113], v[138:141], v[190:193], v[110:113]
	v_mfma_f32_16x16x32_bf16 v[110:113], v[134:137], v[186:189], v[110:113]
	v_mfma_f32_16x16x32_bf16 v[94:97], v[134:137], v[204:207], v[94:97]
	v_mfma_f32_16x16x32_bf16 v[94:97], v[138:141], v[208:211], v[94:97]
	v_mfma_f32_16x16x32_bf16 v[90:93], v[146:149], v[208:211], v[90:93]
	v_mfma_f32_16x16x32_bf16 v[90:93], v[142:145], v[204:207], v[90:93]
	v_mfma_f32_16x16x32_bf16 v[86:89], v[150:153], v[204:207], v[86:89]
	v_mfma_f32_16x16x32_bf16 v[86:89], v[154:157], v[208:211], v[86:89]
	v_mfma_f32_16x16x32_bf16 v[82:85], v[174:177], v[208:211], v[82:85]
	v_mfma_f32_16x16x32_bf16 v[82:85], v[158:161], v[204:207], v[82:85]
	v_mfma_f32_16x16x32_bf16 v[66:69], v[158:161], v[212:215], v[66:69]
	v_mfma_f32_16x16x32_bf16 v[66:69], v[174:177], v[216:219], v[66:69]
	v_mfma_f32_16x16x32_bf16 v[70:73], v[154:157], v[216:219], v[70:73]
	v_mfma_f32_16x16x32_bf16 v[70:73], v[150:153], v[212:215], v[70:73]
	v_mfma_f32_16x16x32_bf16 v[74:77], v[142:145], v[212:215], v[74:77]
	v_mfma_f32_16x16x32_bf16 v[74:77], v[146:149], v[216:219], v[74:77]
	v_mfma_f32_16x16x32_bf16 v[78:81], v[138:141], v[216:219], v[78:81]
	v_mfma_f32_16x16x32_bf16 v[78:81], v[134:137], v[212:215], v[78:81]
	s_setprio 0
	s_barrier
	s_add_u32 s98, s70, 0x80
	s_addc_u32 s99, s71, 0
	s_add_u32 s100, vcc_lo, 0x80
	s_addc_u32 s101, vcc_hi, 0
	s_add_i32 s0, s0, s54
	s_mov_b32 m0, s0
	ds_read_b128 v[178:181], v222 offset:49152
	ds_read_b128 v[182:185], v222 offset:50176
	ds_read_b128 v[186:189], v222 offset:51200
	ds_read_b128 v[190:193], v222 offset:52224
	ds_read_b128 v[204:207], v222 offset:53248
	ds_read_b128 v[208:211], v222 offset:54272
	ds_read_b128 v[212:215], v222 offset:55296
	ds_read_b128 v[216:219], v222 offset:56320
	global_load_lds_dwordx4 v164, s[98:99]
	s_add_i32 m0, s0, 0x2000
	s_add_u32 s44, s70, 0x80080
	s_addc_u32 s45, s71, 0
	s_add_i32 s0, s1, s54
	global_load_lds_dwordx4 v162, s[98:99]
	s_mov_b32 m0, s0
	s_nop 0
	global_load_lds_dwordx4 v164, s[44:45]
	s_add_i32 m0, s0, 0x2000
	s_nop 0
	global_load_lds_dwordx4 v162, s[44:45]
	s_mov_b32 m0, s27
	s_nop 0
	global_load_lds_dwordx4 v164, s[100:101]
	s_mov_b32 m0, s26
	s_nop 0
	global_load_lds_dwordx4 v162, s[100:101]
	s_waitcnt vmcnt(8)
	s_barrier
	s_setprio 1
	s_waitcnt lgkmcnt(0)
	v_mfma_f32_16x16x32_bf16 v[62:65], v[134:137], v[178:181], v[62:65]
	v_mfma_f32_16x16x32_bf16 v[62:65], v[138:141], v[182:185], v[62:65]
	v_mfma_f32_16x16x32_bf16 v[58:61], v[146:149], v[182:185], v[58:61]
	v_mfma_f32_16x16x32_bf16 v[58:61], v[142:145], v[178:181], v[58:61]
	v_mfma_f32_16x16x32_bf16 v[54:57], v[150:153], v[178:181], v[54:57]
	v_mfma_f32_16x16x32_bf16 v[54:57], v[154:157], v[182:185], v[54:57]
	v_mfma_f32_16x16x32_bf16 v[50:53], v[174:177], v[182:185], v[50:53]
	v_mfma_f32_16x16x32_bf16 v[50:53], v[158:161], v[178:181], v[50:53]
	v_mfma_f32_16x16x32_bf16 v[34:37], v[158:161], v[186:189], v[34:37]
	v_mfma_f32_16x16x32_bf16 v[34:37], v[174:177], v[190:193], v[34:37]
	v_mfma_f32_16x16x32_bf16 v[38:41], v[154:157], v[190:193], v[38:41]
	v_mfma_f32_16x16x32_bf16 v[38:41], v[150:153], v[186:189], v[38:41]
	v_mfma_f32_16x16x32_bf16 v[42:45], v[142:145], v[186:189], v[42:45]
	v_mfma_f32_16x16x32_bf16 v[42:45], v[146:149], v[190:193], v[42:45]
	v_mfma_f32_16x16x32_bf16 v[46:49], v[138:141], v[190:193], v[46:49]
	v_mfma_f32_16x16x32_bf16 v[46:49], v[134:137], v[186:189], v[46:49]
	v_mfma_f32_16x16x32_bf16 v[30:33], v[134:137], v[204:207], v[30:33]
	v_mfma_f32_16x16x32_bf16 v[30:33], v[138:141], v[208:211], v[30:33]
	v_mfma_f32_16x16x32_bf16 v[26:29], v[146:149], v[208:211], v[26:29]
	v_mfma_f32_16x16x32_bf16 v[26:29], v[142:145], v[204:207], v[26:29]
	v_mfma_f32_16x16x32_bf16 v[22:25], v[150:153], v[204:207], v[22:25]
	v_mfma_f32_16x16x32_bf16 v[22:25], v[154:157], v[208:211], v[22:25]
	v_mfma_f32_16x16x32_bf16 v[18:21], v[174:177], v[208:211], v[18:21]
	v_mfma_f32_16x16x32_bf16 v[18:21], v[158:161], v[204:207], v[18:21]
	v_mfma_f32_16x16x32_bf16 v[2:5], v[158:161], v[212:215], v[2:5]
	v_mfma_f32_16x16x32_bf16 v[2:5], v[174:177], v[216:219], v[2:5]
	v_mfma_f32_16x16x32_bf16 v[6:9], v[154:157], v[216:219], v[6:9]
	v_mfma_f32_16x16x32_bf16 v[6:9], v[150:153], v[212:215], v[6:9]
	v_mfma_f32_16x16x32_bf16 v[10:13], v[142:145], v[212:215], v[10:13]
	v_mfma_f32_16x16x32_bf16 v[10:13], v[146:149], v[216:219], v[10:13]
	v_mfma_f32_16x16x32_bf16 v[14:17], v[138:141], v[216:219], v[14:17]
	v_mfma_f32_16x16x32_bf16 v[14:17], v[134:137], v[212:215], v[14:17]
	s_setprio 0
	s_barrier
	s_add_i32 s43, s43, 2
	s_add_u32 s76, s76, 0x100
	s_addc_u32 s77, s77, 0
	s_add_u32 s7, s7, 0x100
	s_addc_u32 s41, s41, 0
	s_cmp_gt_u32 s43, 29
	s_cbranch_scc1 .LBB0_288

.LBB0_509:
	s_add_u32 s90, s76, 0x100
	s_addc_u32 s91, s77, 0
	s_and_b64 s[0:1], s[70:71], exec
	s_cselect_b32 vcc_hi, s22, s91
	s_cselect_b32 vcc_lo, s23, s90
	s_cselect_b32 s71, s41, s53
	s_cselect_b32 s70, s44, s51
	s_add_i32 s0, 0, 0x10000
	s_add_i32 s18, 0, 0x14000
	v_add_u32_e32 v114, s0, v1
	v_add_u32_e32 v154, s18, v1
	ds_read_b128 v[78:81], v114
	ds_read_b128 v[90:93], v114 offset:1024
	ds_read_b128 v[102:105], v114 offset:2048
	ds_read_b128 v[114:117], v114 offset:3072
	ds_read_b128 v[126:129], v154
	ds_read_b128 v[134:137], v154 offset:1024
	ds_read_b128 v[142:145], v154 offset:2048
	ds_read_b128 v[154:157], v154 offset:3072
	s_add_i32 m0, s29, 0xc000
	ds_read_b128 v[158:161], v237
	ds_read_b128 v[162:165], v237 offset:1024
	ds_read_b128 v[166:169], v237 offset:2048
	ds_read_b128 v[178:181], v237 offset:3072
	ds_read_b128 v[182:185], v237 offset:4096
	ds_read_b128 v[186:189], v237 offset:5120
	ds_read_b128 v[190:193], v237 offset:6144
	ds_read_b128 v[214:217], v237 offset:7168
	global_load_lds_dwordx4 v210, s[76:77]
	s_add_i32 m0, s29, 0xe000
	s_nop 0
	global_load_lds_dwordx4 v212, s[76:77]
	s_waitcnt vmcnt(8)
	s_barrier
	s_setprio 1
	s_waitcnt lgkmcnt(0)
	v_mfma_f32_16x16x32_bf16 v[174:177], v[78:81], v[158:161], v[174:177]
	v_mfma_f32_16x16x32_bf16 v[174:177], v[90:93], v[162:165], v[174:177]
	v_mfma_f32_16x16x32_bf16 v[170:173], v[114:117], v[162:165], v[170:173]
	v_mfma_f32_16x16x32_bf16 v[170:173], v[102:105], v[158:161], v[170:173]
	v_mfma_f32_16x16x32_bf16 v[150:153], v[126:129], v[158:161], v[150:153]
	v_mfma_f32_16x16x32_bf16 v[150:153], v[134:137], v[162:165], v[150:153]
	v_mfma_f32_16x16x32_bf16 v[146:149], v[154:157], v[162:165], v[146:149]
	v_mfma_f32_16x16x32_bf16 v[146:149], v[142:145], v[158:161], v[146:149]
	v_mfma_f32_16x16x32_bf16 v[118:121], v[142:145], v[166:169], v[118:121]
	v_mfma_f32_16x16x32_bf16 v[118:121], v[154:157], v[178:181], v[118:121]
	v_mfma_f32_16x16x32_bf16 v[122:125], v[134:137], v[178:181], v[122:125]
	v_mfma_f32_16x16x32_bf16 v[122:125], v[126:129], v[166:169], v[122:125]
	v_mfma_f32_16x16x32_bf16 v[130:133], v[102:105], v[166:169], v[130:133]
	v_mfma_f32_16x16x32_bf16 v[130:133], v[114:117], v[178:181], v[130:133]
	v_mfma_f32_16x16x32_bf16 v[138:141], v[90:93], v[178:181], v[138:141]
	v_mfma_f32_16x16x32_bf16 v[138:141], v[78:81], v[166:169], v[138:141]
	v_mfma_f32_16x16x32_bf16 v[110:113], v[78:81], v[182:185], v[110:113]
	v_mfma_f32_16x16x32_bf16 v[110:113], v[90:93], v[186:189], v[110:113]
	v_mfma_f32_16x16x32_bf16 v[106:109], v[114:117], v[186:189], v[106:109]
	v_mfma_f32_16x16x32_bf16 v[106:109], v[102:105], v[182:185], v[106:109]
	v_mfma_f32_16x16x32_bf16 v[98:101], v[126:129], v[182:185], v[98:101]
	v_mfma_f32_16x16x32_bf16 v[98:101], v[134:137], v[186:189], v[98:101]
	v_mfma_f32_16x16x32_bf16 v[94:97], v[154:157], v[186:189], v[94:97]
	v_mfma_f32_16x16x32_bf16 v[94:97], v[142:145], v[182:185], v[94:97]
	v_mfma_f32_16x16x32_bf16 v[66:69], v[142:145], v[190:193], v[66:69]
	v_mfma_f32_16x16x32_bf16 v[66:69], v[154:157], v[214:217], v[66:69]
	v_mfma_f32_16x16x32_bf16 v[74:77], v[134:137], v[214:217], v[74:77]
	v_mfma_f32_16x16x32_bf16 v[74:77], v[126:129], v[190:193], v[74:77]
	v_mfma_f32_16x16x32_bf16 v[82:85], v[102:105], v[190:193], v[82:85]
	v_mfma_f32_16x16x32_bf16 v[82:85], v[114:117], v[214:217], v[82:85]
	v_mfma_f32_16x16x32_bf16 v[86:89], v[90:93], v[214:217], v[86:89]
	v_mfma_f32_16x16x32_bf16 v[86:89], v[78:81], v[190:193], v[86:89]
	s_setprio 0
	s_barrier
	s_add_i32 s0, s0, s28
	s_mov_b32 m0, s0
	ds_read_b128 v[158:161], v237 offset:16384
	ds_read_b128 v[162:165], v237 offset:17408
	ds_read_b128 v[166:169], v237 offset:18432
	ds_read_b128 v[178:181], v237 offset:19456
	ds_read_b128 v[182:185], v237 offset:20480
	ds_read_b128 v[186:189], v237 offset:21504
	ds_read_b128 v[190:193], v237 offset:22528
	ds_read_b128 v[214:217], v237 offset:23552
	global_load_lds_dwordx4 v194, s[70:71]
	s_add_i32 m0, s0, 0x2000
	s_add_u32 s0, s70, 0x80000
	s_addc_u32 s1, s71, 0
	s_add_i32 s18, s18, s28
	global_load_lds_dwordx4 v204, s[70:71]
	s_mov_b32 m0, s18
	s_nop 0
	global_load_lds_dwordx4 v194, s[0:1]
	s_add_i32 m0, s18, 0x2000
	s_nop 0
	global_load_lds_dwordx4 v204, s[0:1]
	s_mov_b32 m0, s29
	s_nop 0
	global_load_lds_dwordx4 v194, vcc
	s_mov_b32 m0, s31
	s_nop 0
	global_load_lds_dwordx4 v204, vcc
	s_waitcnt vmcnt(8)
	s_barrier
	s_setprio 1
	s_waitcnt lgkmcnt(0)
	v_mfma_f32_16x16x32_bf16 v[62:65], v[78:81], v[158:161], v[62:65]
	v_mfma_f32_16x16x32_bf16 v[62:65], v[90:93], v[162:165], v[62:65]
	v_mfma_f32_16x16x32_bf16 v[58:61], v[114:117], v[162:165], v[58:61]
	v_mfma_f32_16x16x32_bf16 v[58:61], v[102:105], v[158:161], v[58:61]
	v_mfma_f32_16x16x32_bf16 v[54:57], v[126:129], v[158:161], v[54:57]
	v_mfma_f32_16x16x32_bf16 v[54:57], v[134:137], v[162:165], v[54:57]
	v_mfma_f32_16x16x32_bf16 v[50:53], v[154:157], v[162:165], v[50:53]
	v_mfma_f32_16x16x32_bf16 v[50:53], v[142:145], v[158:161], v[50:53]
	v_mfma_f32_16x16x32_bf16 v[34:37], v[142:145], v[166:169], v[34:37]
	v_mfma_f32_16x16x32_bf16 v[34:37], v[154:157], v[178:181], v[34:37]
	v_mfma_f32_16x16x32_bf16 v[38:41], v[134:137], v[178:181], v[38:41]
	v_mfma_f32_16x16x32_bf16 v[38:41], v[126:129], v[166:169], v[38:41]
	v_mfma_f32_16x16x32_bf16 v[42:45], v[102:105], v[166:169], v[42:45]
	v_mfma_f32_16x16x32_bf16 v[42:45], v[114:117], v[178:181], v[42:45]
	v_mfma_f32_16x16x32_bf16 v[46:49], v[90:93], v[178:181], v[46:49]
	v_mfma_f32_16x16x32_bf16 v[46:49], v[78:81], v[166:169], v[46:49]
	v_mfma_f32_16x16x32_bf16 v[30:33], v[78:81], v[182:185], v[30:33]
	v_mfma_f32_16x16x32_bf16 v[30:33], v[90:93], v[186:189], v[30:33]
	v_mfma_f32_16x16x32_bf16 v[26:29], v[114:117], v[186:189], v[26:29]
	v_mfma_f32_16x16x32_bf16 v[26:29], v[102:105], v[182:185], v[26:29]
	v_mfma_f32_16x16x32_bf16 v[22:25], v[126:129], v[182:185], v[22:25]
	v_mfma_f32_16x16x32_bf16 v[22:25], v[134:137], v[186:189], v[22:25]
	v_mfma_f32_16x16x32_bf16 v[18:21], v[154:157], v[186:189], v[18:21]
	v_mfma_f32_16x16x32_bf16 v[18:21], v[142:145], v[182:185], v[18:21]
	v_mfma_f32_16x16x32_bf16 v[2:5], v[142:145], v[190:193], v[2:5]
	v_mfma_f32_16x16x32_bf16 v[2:5], v[154:157], v[214:217], v[2:5]
	v_mfma_f32_16x16x32_bf16 v[6:9], v[134:137], v[214:217], v[6:9]
	v_mfma_f32_16x16x32_bf16 v[6:9], v[126:129], v[190:193], v[6:9]
	v_mfma_f32_16x16x32_bf16 v[10:13], v[102:105], v[190:193], v[10:13]
	v_mfma_f32_16x16x32_bf16 v[10:13], v[114:117], v[214:217], v[10:13]
	v_mfma_f32_16x16x32_bf16 v[14:17], v[90:93], v[214:217], v[14:17]
	v_mfma_f32_16x16x32_bf16 v[14:17], v[78:81], v[190:193], v[14:17]
	s_setprio 0
	s_barrier
	s_add_i32 s18, 0, 0x18000
	s_add_i32 s19, 0, 0x1c000
	v_add_u32_e32 v114, s18, v1
	v_add_u32_e32 v154, s19, v1
	ds_read_b128 v[78:81], v114
	ds_read_b128 v[90:93], v114 offset:1024
	ds_read_b128 v[102:105], v114 offset:2048
	ds_read_b128 v[114:117], v114 offset:3072
	ds_read_b128 v[126:129], v154
	ds_read_b128 v[134:137], v154 offset:1024
	ds_read_b128 v[142:145], v154 offset:2048
	ds_read_b128 v[154:157], v154 offset:3072
	s_add_u32 s0, vcc_lo, 0x80000
	s_addc_u32 s1, vcc_hi, 0
	s_mov_b32 m0, s33
	ds_read_b128 v[158:161], v237 offset:32768
	ds_read_b128 v[162:165], v237 offset:33792
	ds_read_b128 v[166:169], v237 offset:34816
	ds_read_b128 v[178:181], v237 offset:35840
	ds_read_b128 v[182:185], v237 offset:36864
	ds_read_b128 v[186:189], v237 offset:37888
	ds_read_b128 v[190:193], v237 offset:38912
	ds_read_b128 v[214:217], v237 offset:39936
	global_load_lds_dwordx4 v194, s[0:1]
	s_mov_b32 m0, s43
	s_nop 0
	global_load_lds_dwordx4 v204, s[0:1]
	s_waitcnt vmcnt(8)
	s_barrier
	s_setprio 1
	s_waitcnt lgkmcnt(0)
	v_mfma_f32_16x16x32_bf16 v[174:177], v[78:81], v[158:161], v[174:177]
	v_mfma_f32_16x16x32_bf16 v[174:177], v[90:93], v[162:165], v[174:177]
	v_mfma_f32_16x16x32_bf16 v[170:173], v[114:117], v[162:165], v[170:173]
	v_mfma_f32_16x16x32_bf16 v[170:173], v[102:105], v[158:161], v[170:173]
	v_mfma_f32_16x16x32_bf16 v[150:153], v[126:129], v[158:161], v[150:153]
	v_mfma_f32_16x16x32_bf16 v[150:153], v[134:137], v[162:165], v[150:153]
	v_mfma_f32_16x16x32_bf16 v[146:149], v[154:157], v[162:165], v[146:149]
	v_mfma_f32_16x16x32_bf16 v[146:149], v[142:145], v[158:161], v[146:149]
	v_mfma_f32_16x16x32_bf16 v[118:121], v[142:145], v[166:169], v[118:121]
	v_mfma_f32_16x16x32_bf16 v[118:121], v[154:157], v[178:181], v[118:121]
	v_mfma_f32_16x16x32_bf16 v[122:125], v[134:137], v[178:181], v[122:125]
	v_mfma_f32_16x16x32_bf16 v[122:125], v[126:129], v[166:169], v[122:125]
	v_mfma_f32_16x16x32_bf16 v[130:133], v[102:105], v[166:169], v[130:133]
	v_mfma_f32_16x16x32_bf16 v[130:133], v[114:117], v[178:181], v[130:133]
	v_mfma_f32_16x16x32_bf16 v[138:141], v[90:93], v[178:181], v[138:141]
	v_mfma_f32_16x16x32_bf16 v[138:141], v[78:81], v[166:169], v[138:141]
	v_mfma_f32_16x16x32_bf16 v[110:113], v[78:81], v[182:185], v[110:113]
	v_mfma_f32_16x16x32_bf16 v[110:113], v[90:93], v[186:189], v[110:113]
	v_mfma_f32_16x16x32_bf16 v[106:109], v[114:117], v[186:189], v[106:109]
	v_mfma_f32_16x16x32_bf16 v[106:109], v[102:105], v[182:185], v[106:109]
	v_mfma_f32_16x16x32_bf16 v[98:101], v[126:129], v[182:185], v[98:101]
	v_mfma_f32_16x16x32_bf16 v[98:101], v[134:137], v[186:189], v[98:101]
	v_mfma_f32_16x16x32_bf16 v[94:97], v[154:157], v[186:189], v[94:97]
	v_mfma_f32_16x16x32_bf16 v[94:97], v[142:145], v[182:185], v[94:97]
	v_mfma_f32_16x16x32_bf16 v[66:69], v[142:145], v[190:193], v[66:69]
	v_mfma_f32_16x16x32_bf16 v[66:69], v[154:157], v[214:217], v[66:69]
	v_mfma_f32_16x16x32_bf16 v[74:77], v[134:137], v[214:217], v[74:77]
	v_mfma_f32_16x16x32_bf16 v[74:77], v[126:129], v[190:193], v[74:77]
	v_mfma_f32_16x16x32_bf16 v[82:85], v[102:105], v[190:193], v[82:85]
	v_mfma_f32_16x16x32_bf16 v[82:85], v[114:117], v[214:217], v[82:85]
	v_mfma_f32_16x16x32_bf16 v[86:89], v[90:93], v[214:217], v[86:89]
	v_mfma_f32_16x16x32_bf16 v[86:89], v[78:81], v[190:193], v[86:89]
	s_setprio 0
	s_barrier
	s_add_u32 s98, s70, 0x80
	s_addc_u32 s99, s71, 0
	s_add_u32 s100, vcc_lo, 0x80
	s_addc_u32 s101, vcc_hi, 0
	s_add_i32 s0, s18, s28
	s_mov_b32 m0, s0
	ds_read_b128 v[158:161], v237 offset:49152
	ds_read_b128 v[162:165], v237 offset:50176
	ds_read_b128 v[166:169], v237 offset:51200
	ds_read_b128 v[178:181], v237 offset:52224
	ds_read_b128 v[182:185], v237 offset:53248
	ds_read_b128 v[186:189], v237 offset:54272
	ds_read_b128 v[190:193], v237 offset:55296
	ds_read_b128 v[214:217], v237 offset:56320
	global_load_lds_dwordx4 v194, s[98:99]
	s_add_i32 m0, s0, 0x2000
	s_add_u32 s0, s70, 0x80080
	s_addc_u32 s1, s71, 0
	s_add_i32 s18, s19, s28
	global_load_lds_dwordx4 v204, s[98:99]
	s_mov_b32 m0, s18
	s_nop 0
	global_load_lds_dwordx4 v194, s[0:1]
	s_add_i32 m0, s18, 0x2000
	s_nop 0
	global_load_lds_dwordx4 v204, s[0:1]
	s_mov_b32 m0, s68
	s_nop 0
	global_load_lds_dwordx4 v194, s[100:101]
	s_mov_b32 m0, s79
	s_nop 0
	global_load_lds_dwordx4 v204, s[100:101]
	s_waitcnt vmcnt(8)
	s_barrier
	s_setprio 1
	s_waitcnt lgkmcnt(0)
	v_mfma_f32_16x16x32_bf16 v[62:65], v[78:81], v[158:161], v[62:65]
	v_mfma_f32_16x16x32_bf16 v[62:65], v[90:93], v[162:165], v[62:65]
	v_mfma_f32_16x16x32_bf16 v[58:61], v[114:117], v[162:165], v[58:61]
	v_mfma_f32_16x16x32_bf16 v[58:61], v[102:105], v[158:161], v[58:61]
	v_mfma_f32_16x16x32_bf16 v[54:57], v[126:129], v[158:161], v[54:57]
	v_mfma_f32_16x16x32_bf16 v[54:57], v[134:137], v[162:165], v[54:57]
	v_mfma_f32_16x16x32_bf16 v[50:53], v[154:157], v[162:165], v[50:53]
	v_mfma_f32_16x16x32_bf16 v[50:53], v[142:145], v[158:161], v[50:53]
	v_mfma_f32_16x16x32_bf16 v[34:37], v[142:145], v[166:169], v[34:37]
	v_mfma_f32_16x16x32_bf16 v[34:37], v[154:157], v[178:181], v[34:37]
	v_mfma_f32_16x16x32_bf16 v[38:41], v[134:137], v[178:181], v[38:41]
	v_mfma_f32_16x16x32_bf16 v[38:41], v[126:129], v[166:169], v[38:41]
	v_mfma_f32_16x16x32_bf16 v[42:45], v[102:105], v[166:169], v[42:45]
	v_mfma_f32_16x16x32_bf16 v[42:45], v[114:117], v[178:181], v[42:45]
	v_mfma_f32_16x16x32_bf16 v[46:49], v[90:93], v[178:181], v[46:49]
	v_mfma_f32_16x16x32_bf16 v[46:49], v[78:81], v[166:169], v[46:49]
	v_mfma_f32_16x16x32_bf16 v[30:33], v[78:81], v[182:185], v[30:33]
	v_mfma_f32_16x16x32_bf16 v[30:33], v[90:93], v[186:189], v[30:33]
	v_mfma_f32_16x16x32_bf16 v[26:29], v[114:117], v[186:189], v[26:29]
	v_mfma_f32_16x16x32_bf16 v[26:29], v[102:105], v[182:185], v[26:29]
	v_mfma_f32_16x16x32_bf16 v[22:25], v[126:129], v[182:185], v[22:25]
	v_mfma_f32_16x16x32_bf16 v[22:25], v[134:137], v[186:189], v[22:25]
	v_mfma_f32_16x16x32_bf16 v[18:21], v[154:157], v[186:189], v[18:21]
	v_mfma_f32_16x16x32_bf16 v[18:21], v[142:145], v[182:185], v[18:21]
	v_mfma_f32_16x16x32_bf16 v[2:5], v[142:145], v[190:193], v[2:5]
	v_mfma_f32_16x16x32_bf16 v[2:5], v[154:157], v[214:217], v[2:5]
	v_mfma_f32_16x16x32_bf16 v[6:9], v[134:137], v[214:217], v[6:9]
	v_mfma_f32_16x16x32_bf16 v[6:9], v[126:129], v[190:193], v[6:9]
	v_mfma_f32_16x16x32_bf16 v[10:13], v[102:105], v[190:193], v[10:13]
	v_mfma_f32_16x16x32_bf16 v[10:13], v[114:117], v[214:217], v[10:13]
	v_mfma_f32_16x16x32_bf16 v[14:17], v[90:93], v[214:217], v[14:17]
	v_mfma_f32_16x16x32_bf16 v[14:17], v[78:81], v[190:193], v[14:17]
	s_setprio 0
	s_barrier
	s_add_i32 s57, s57, 2
	s_add_u32 s51, s51, 0x100
	s_addc_u32 s53, s53, 0
	s_cmp_gt_u32 s57, 29
	s_mov_b64 s[76:77], s[90:91]
	s_cbranch_scc1 .LBB0_512

.LBB0_581:
	s_add_u32 s18, s62, 0xfff80080
	s_addc_u32 s19, s63, -1
	s_and_b64 s[0:1], s[64:65], exec
	s_cselect_b32 s71, s22, s19
	s_cselect_b32 s70, s23, s18
	s_cselect_b32 s65, s39, s58
	s_cselect_b32 s64, s47, s53
	s_add_i32 s0, 0, 0x10000
	v_add_u32_e32 v153, s0, v1
	s_add_i32 s18, 0, 0x14000
	ds_read_b128 v[144:147], v153
	ds_read_b128 v[148:151], v153 offset:1024
	ds_read_b128 v[154:157], v153 offset:2048
	ds_read_b128 v[158:161], v153 offset:3072
	v_add_u32_e32 v153, s18, v1
	ds_read_b128 v[162:165], v153
	ds_read_b128 v[166:169], v153 offset:1024
	ds_read_b128 v[170:173], v153 offset:2048
	ds_read_b128 v[174:177], v153 offset:3072
	s_add_i32 m0, s29, 0xc000
	ds_read_b128 v[178:181], v152
	ds_read_b128 v[182:185], v152 offset:1024
	ds_read_b128 v[186:189], v152 offset:2048
	ds_read_b128 v[190:193], v152 offset:3072
	ds_read_b128 v[204:207], v152 offset:4096
	ds_read_b128 v[208:211], v152 offset:5120
	ds_read_b128 v[212:215], v152 offset:6144
	ds_read_b128 v[216:219], v152 offset:7168
	global_load_lds_dwordx4 v136, s[62:63]
	s_add_i32 m0, s29, 0xe000
	s_nop 0
	global_load_lds_dwordx4 v138, s[62:63]
	s_waitcnt vmcnt(8)
	s_barrier
	s_setprio 1
	s_waitcnt lgkmcnt(0)
	v_mfma_f32_16x16x32_bf16 v[126:129], v[144:147], v[178:181], v[126:129]
	v_mfma_f32_16x16x32_bf16 v[126:129], v[148:151], v[182:185], v[126:129]
	v_mfma_f32_16x16x32_bf16 v[122:125], v[158:161], v[182:185], v[122:125]
	v_mfma_f32_16x16x32_bf16 v[122:125], v[154:157], v[178:181], v[122:125]
	v_mfma_f32_16x16x32_bf16 v[118:121], v[162:165], v[178:181], v[118:121]
	v_mfma_f32_16x16x32_bf16 v[118:121], v[166:169], v[182:185], v[118:121]
	v_mfma_f32_16x16x32_bf16 v[114:117], v[174:177], v[182:185], v[114:117]
	v_mfma_f32_16x16x32_bf16 v[114:117], v[170:173], v[178:181], v[114:117]
	v_mfma_f32_16x16x32_bf16 v[98:101], v[170:173], v[186:189], v[98:101]
	v_mfma_f32_16x16x32_bf16 v[98:101], v[174:177], v[190:193], v[98:101]
	v_mfma_f32_16x16x32_bf16 v[102:105], v[166:169], v[190:193], v[102:105]
	v_mfma_f32_16x16x32_bf16 v[102:105], v[162:165], v[186:189], v[102:105]
	v_mfma_f32_16x16x32_bf16 v[106:109], v[154:157], v[186:189], v[106:109]
	v_mfma_f32_16x16x32_bf16 v[106:109], v[158:161], v[190:193], v[106:109]
	v_mfma_f32_16x16x32_bf16 v[110:113], v[148:151], v[190:193], v[110:113]
	v_mfma_f32_16x16x32_bf16 v[110:113], v[144:147], v[186:189], v[110:113]
	v_mfma_f32_16x16x32_bf16 v[94:97], v[144:147], v[204:207], v[94:97]
	v_mfma_f32_16x16x32_bf16 v[94:97], v[148:151], v[208:211], v[94:97]
	v_mfma_f32_16x16x32_bf16 v[90:93], v[158:161], v[208:211], v[90:93]
	v_mfma_f32_16x16x32_bf16 v[90:93], v[154:157], v[204:207], v[90:93]
	v_mfma_f32_16x16x32_bf16 v[86:89], v[162:165], v[204:207], v[86:89]
	v_mfma_f32_16x16x32_bf16 v[86:89], v[166:169], v[208:211], v[86:89]
	v_mfma_f32_16x16x32_bf16 v[82:85], v[174:177], v[208:211], v[82:85]
	v_mfma_f32_16x16x32_bf16 v[82:85], v[170:173], v[204:207], v[82:85]
	v_mfma_f32_16x16x32_bf16 v[66:69], v[170:173], v[212:215], v[66:69]
	v_mfma_f32_16x16x32_bf16 v[66:69], v[174:177], v[216:219], v[66:69]
	v_mfma_f32_16x16x32_bf16 v[70:73], v[166:169], v[216:219], v[70:73]
	v_mfma_f32_16x16x32_bf16 v[70:73], v[162:165], v[212:215], v[70:73]
	v_mfma_f32_16x16x32_bf16 v[74:77], v[154:157], v[212:215], v[74:77]
	v_mfma_f32_16x16x32_bf16 v[74:77], v[158:161], v[216:219], v[74:77]
	v_mfma_f32_16x16x32_bf16 v[78:81], v[148:151], v[216:219], v[78:81]
	v_mfma_f32_16x16x32_bf16 v[78:81], v[144:147], v[212:215], v[78:81]
	s_setprio 0
	s_barrier
	s_add_i32 s0, s0, s28
	s_mov_b32 m0, s0
	ds_read_b128 v[178:181], v152 offset:16384
	ds_read_b128 v[182:185], v152 offset:17408
	ds_read_b128 v[186:189], v152 offset:18432
	ds_read_b128 v[190:193], v152 offset:19456
	ds_read_b128 v[204:207], v152 offset:20480
	ds_read_b128 v[208:211], v152 offset:21504
	ds_read_b128 v[212:215], v152 offset:22528
	ds_read_b128 v[216:219], v152 offset:23552
	global_load_lds_dwordx4 v194, s[64:65]
	s_add_i32 m0, s0, 0x2000
	s_add_u32 s0, s64, 0x80000
	s_addc_u32 s1, s65, 0
	s_add_i32 s18, s18, s28
	global_load_lds_dwordx4 v130, s[64:65]
	s_mov_b32 m0, s18
	s_nop 0
	global_load_lds_dwordx4 v194, s[0:1]
	s_add_i32 m0, s18, 0x2000
	s_nop 0
	global_load_lds_dwordx4 v130, s[0:1]
	s_mov_b32 m0, s29
	s_nop 0
	global_load_lds_dwordx4 v194, s[70:71]
	s_mov_b32 m0, s31
	s_nop 0
	global_load_lds_dwordx4 v130, s[70:71]
	s_waitcnt vmcnt(8)
	s_barrier
	s_setprio 1
	s_waitcnt lgkmcnt(0)
	v_mfma_f32_16x16x32_bf16 v[62:65], v[144:147], v[178:181], v[62:65]
	v_mfma_f32_16x16x32_bf16 v[62:65], v[148:151], v[182:185], v[62:65]
	v_mfma_f32_16x16x32_bf16 v[58:61], v[158:161], v[182:185], v[58:61]
	v_mfma_f32_16x16x32_bf16 v[58:61], v[154:157], v[178:181], v[58:61]
	v_mfma_f32_16x16x32_bf16 v[54:57], v[162:165], v[178:181], v[54:57]
	v_mfma_f32_16x16x32_bf16 v[54:57], v[166:169], v[182:185], v[54:57]
	v_mfma_f32_16x16x32_bf16 v[50:53], v[174:177], v[182:185], v[50:53]
	v_mfma_f32_16x16x32_bf16 v[50:53], v[170:173], v[178:181], v[50:53]
	v_mfma_f32_16x16x32_bf16 v[34:37], v[170:173], v[186:189], v[34:37]
	v_mfma_f32_16x16x32_bf16 v[34:37], v[174:177], v[190:193], v[34:37]
	v_mfma_f32_16x16x32_bf16 v[38:41], v[166:169], v[190:193], v[38:41]
	v_mfma_f32_16x16x32_bf16 v[38:41], v[162:165], v[186:189], v[38:41]
	v_mfma_f32_16x16x32_bf16 v[42:45], v[154:157], v[186:189], v[42:45]
	v_mfma_f32_16x16x32_bf16 v[42:45], v[158:161], v[190:193], v[42:45]
	v_mfma_f32_16x16x32_bf16 v[46:49], v[148:151], v[190:193], v[46:49]
	v_mfma_f32_16x16x32_bf16 v[46:49], v[144:147], v[186:189], v[46:49]
	v_mfma_f32_16x16x32_bf16 v[30:33], v[144:147], v[204:207], v[30:33]
	v_mfma_f32_16x16x32_bf16 v[30:33], v[148:151], v[208:211], v[30:33]
	v_mfma_f32_16x16x32_bf16 v[26:29], v[158:161], v[208:211], v[26:29]
	v_mfma_f32_16x16x32_bf16 v[26:29], v[154:157], v[204:207], v[26:29]
	v_mfma_f32_16x16x32_bf16 v[22:25], v[162:165], v[204:207], v[22:25]
	v_mfma_f32_16x16x32_bf16 v[22:25], v[166:169], v[208:211], v[22:25]
	v_mfma_f32_16x16x32_bf16 v[18:21], v[174:177], v[208:211], v[18:21]
	v_mfma_f32_16x16x32_bf16 v[18:21], v[170:173], v[204:207], v[18:21]
	v_mfma_f32_16x16x32_bf16 v[2:5], v[170:173], v[212:215], v[2:5]
	v_mfma_f32_16x16x32_bf16 v[2:5], v[174:177], v[216:219], v[2:5]
	v_mfma_f32_16x16x32_bf16 v[6:9], v[166:169], v[216:219], v[6:9]
	v_mfma_f32_16x16x32_bf16 v[6:9], v[162:165], v[212:215], v[6:9]
	v_mfma_f32_16x16x32_bf16 v[10:13], v[154:157], v[212:215], v[10:13]
	v_mfma_f32_16x16x32_bf16 v[10:13], v[158:161], v[216:219], v[10:13]
	v_mfma_f32_16x16x32_bf16 v[14:17], v[148:151], v[216:219], v[14:17]
	v_mfma_f32_16x16x32_bf16 v[14:17], v[144:147], v[212:215], v[14:17]
	s_setprio 0
	s_barrier
	s_add_i32 s18, 0, 0x18000
	v_add_u32_e32 v153, s18, v1
	s_add_i32 s19, 0, 0x1c000
	ds_read_b128 v[144:147], v153
	ds_read_b128 v[148:151], v153 offset:1024
	ds_read_b128 v[154:157], v153 offset:2048
	ds_read_b128 v[158:161], v153 offset:3072
	v_add_u32_e32 v153, s19, v1
	ds_read_b128 v[162:165], v153
	ds_read_b128 v[166:169], v153 offset:1024
	ds_read_b128 v[170:173], v153 offset:2048
	ds_read_b128 v[174:177], v153 offset:3072
	s_add_u32 s0, s70, 0x80000
	s_addc_u32 s1, s71, 0
	s_mov_b32 m0, s33
	ds_read_b128 v[178:181], v152 offset:32768
	ds_read_b128 v[182:185], v152 offset:33792
	ds_read_b128 v[186:189], v152 offset:34816
	ds_read_b128 v[190:193], v152 offset:35840
	ds_read_b128 v[204:207], v152 offset:36864
	ds_read_b128 v[208:211], v152 offset:37888
	ds_read_b128 v[212:215], v152 offset:38912
	ds_read_b128 v[216:219], v152 offset:39936
	global_load_lds_dwordx4 v194, s[0:1]
	s_mov_b32 m0, s40
	s_nop 0
	global_load_lds_dwordx4 v130, s[0:1]
	s_waitcnt vmcnt(8)
	s_barrier
	s_setprio 1
	s_waitcnt lgkmcnt(0)
	v_mfma_f32_16x16x32_bf16 v[126:129], v[144:147], v[178:181], v[126:129]
	v_mfma_f32_16x16x32_bf16 v[126:129], v[148:151], v[182:185], v[126:129]
	v_mfma_f32_16x16x32_bf16 v[122:125], v[158:161], v[182:185], v[122:125]
	v_mfma_f32_16x16x32_bf16 v[122:125], v[154:157], v[178:181], v[122:125]
	v_mfma_f32_16x16x32_bf16 v[118:121], v[162:165], v[178:181], v[118:121]
	v_mfma_f32_16x16x32_bf16 v[118:121], v[166:169], v[182:185], v[118:121]
	v_mfma_f32_16x16x32_bf16 v[114:117], v[174:177], v[182:185], v[114:117]
	v_mfma_f32_16x16x32_bf16 v[114:117], v[170:173], v[178:181], v[114:117]
	v_mfma_f32_16x16x32_bf16 v[98:101], v[170:173], v[186:189], v[98:101]
	v_mfma_f32_16x16x32_bf16 v[98:101], v[174:177], v[190:193], v[98:101]
	v_mfma_f32_16x16x32_bf16 v[102:105], v[166:169], v[190:193], v[102:105]
	v_mfma_f32_16x16x32_bf16 v[102:105], v[162:165], v[186:189], v[102:105]
	v_mfma_f32_16x16x32_bf16 v[106:109], v[154:157], v[186:189], v[106:109]
	v_mfma_f32_16x16x32_bf16 v[106:109], v[158:161], v[190:193], v[106:109]
	v_mfma_f32_16x16x32_bf16 v[110:113], v[148:151], v[190:193], v[110:113]
	v_mfma_f32_16x16x32_bf16 v[110:113], v[144:147], v[186:189], v[110:113]
	v_mfma_f32_16x16x32_bf16 v[94:97], v[144:147], v[204:207], v[94:97]
	v_mfma_f32_16x16x32_bf16 v[94:97], v[148:151], v[208:211], v[94:97]
	v_mfma_f32_16x16x32_bf16 v[90:93], v[158:161], v[208:211], v[90:93]
	v_mfma_f32_16x16x32_bf16 v[90:93], v[154:157], v[204:207], v[90:93]
	v_mfma_f32_16x16x32_bf16 v[86:89], v[162:165], v[204:207], v[86:89]
	v_mfma_f32_16x16x32_bf16 v[86:89], v[166:169], v[208:211], v[86:89]
	v_mfma_f32_16x16x32_bf16 v[82:85], v[174:177], v[208:211], v[82:85]
	v_mfma_f32_16x16x32_bf16 v[82:85], v[170:173], v[204:207], v[82:85]
	v_mfma_f32_16x16x32_bf16 v[66:69], v[170:173], v[212:215], v[66:69]
	v_mfma_f32_16x16x32_bf16 v[66:69], v[174:177], v[216:219], v[66:69]
	v_mfma_f32_16x16x32_bf16 v[70:73], v[166:169], v[216:219], v[70:73]
	v_mfma_f32_16x16x32_bf16 v[70:73], v[162:165], v[212:215], v[70:73]
	v_mfma_f32_16x16x32_bf16 v[74:77], v[154:157], v[212:215], v[74:77]
	v_mfma_f32_16x16x32_bf16 v[74:77], v[158:161], v[216:219], v[74:77]
	v_mfma_f32_16x16x32_bf16 v[78:81], v[148:151], v[216:219], v[78:81]
	v_mfma_f32_16x16x32_bf16 v[78:81], v[144:147], v[212:215], v[78:81]
	s_setprio 0
	s_barrier
	s_add_u32 s98, s64, 0x80
	s_addc_u32 s99, s65, 0
	s_add_u32 s100, s70, 0x80
	s_addc_u32 s101, s71, 0
	s_add_i32 s0, s18, s28
	s_mov_b32 m0, s0
	ds_read_b128 v[178:181], v152 offset:49152
	ds_read_b128 v[182:185], v152 offset:50176
	ds_read_b128 v[186:189], v152 offset:51200
	ds_read_b128 v[190:193], v152 offset:52224
	ds_read_b128 v[204:207], v152 offset:53248
	ds_read_b128 v[208:211], v152 offset:54272
	ds_read_b128 v[212:215], v152 offset:55296
	ds_read_b128 v[216:219], v152 offset:56320
	global_load_lds_dwordx4 v194, s[98:99]
	s_add_i32 m0, s0, 0x2000
	s_add_u32 s0, s64, 0x80080
	s_addc_u32 s1, s65, 0
	s_add_i32 s18, s19, s28
	global_load_lds_dwordx4 v130, s[98:99]
	s_mov_b32 m0, s18
	s_nop 0
	global_load_lds_dwordx4 v194, s[0:1]
	s_add_i32 m0, s18, 0x2000
	s_nop 0
	global_load_lds_dwordx4 v130, s[0:1]
	s_mov_b32 m0, s54
	s_nop 0
	global_load_lds_dwordx4 v194, s[100:101]
	s_mov_b32 m0, s57
	s_nop 0
	global_load_lds_dwordx4 v130, s[100:101]
	s_waitcnt vmcnt(8)
	s_barrier
	s_setprio 1
	s_waitcnt lgkmcnt(0)
	v_mfma_f32_16x16x32_bf16 v[62:65], v[144:147], v[178:181], v[62:65]
	v_mfma_f32_16x16x32_bf16 v[62:65], v[148:151], v[182:185], v[62:65]
	v_mfma_f32_16x16x32_bf16 v[58:61], v[158:161], v[182:185], v[58:61]
	v_mfma_f32_16x16x32_bf16 v[58:61], v[154:157], v[178:181], v[58:61]
	v_mfma_f32_16x16x32_bf16 v[54:57], v[162:165], v[178:181], v[54:57]
	v_mfma_f32_16x16x32_bf16 v[54:57], v[166:169], v[182:185], v[54:57]
	v_mfma_f32_16x16x32_bf16 v[50:53], v[174:177], v[182:185], v[50:53]
	v_mfma_f32_16x16x32_bf16 v[50:53], v[170:173], v[178:181], v[50:53]
	v_mfma_f32_16x16x32_bf16 v[34:37], v[170:173], v[186:189], v[34:37]
	v_mfma_f32_16x16x32_bf16 v[34:37], v[174:177], v[190:193], v[34:37]
	v_mfma_f32_16x16x32_bf16 v[38:41], v[166:169], v[190:193], v[38:41]
	v_mfma_f32_16x16x32_bf16 v[38:41], v[162:165], v[186:189], v[38:41]
	v_mfma_f32_16x16x32_bf16 v[42:45], v[154:157], v[186:189], v[42:45]
	v_mfma_f32_16x16x32_bf16 v[42:45], v[158:161], v[190:193], v[42:45]
	v_mfma_f32_16x16x32_bf16 v[46:49], v[148:151], v[190:193], v[46:49]
	v_mfma_f32_16x16x32_bf16 v[46:49], v[144:147], v[186:189], v[46:49]
	v_mfma_f32_16x16x32_bf16 v[30:33], v[144:147], v[204:207], v[30:33]
	v_mfma_f32_16x16x32_bf16 v[30:33], v[148:151], v[208:211], v[30:33]
	v_mfma_f32_16x16x32_bf16 v[26:29], v[158:161], v[208:211], v[26:29]
	v_mfma_f32_16x16x32_bf16 v[26:29], v[154:157], v[204:207], v[26:29]
	v_mfma_f32_16x16x32_bf16 v[22:25], v[162:165], v[204:207], v[22:25]
	v_mfma_f32_16x16x32_bf16 v[22:25], v[166:169], v[208:211], v[22:25]
	v_mfma_f32_16x16x32_bf16 v[18:21], v[174:177], v[208:211], v[18:21]
	v_mfma_f32_16x16x32_bf16 v[18:21], v[170:173], v[204:207], v[18:21]
	v_mfma_f32_16x16x32_bf16 v[2:5], v[170:173], v[212:215], v[2:5]
	v_mfma_f32_16x16x32_bf16 v[2:5], v[174:177], v[216:219], v[2:5]
	v_mfma_f32_16x16x32_bf16 v[6:9], v[166:169], v[216:219], v[6:9]
	v_mfma_f32_16x16x32_bf16 v[6:9], v[162:165], v[212:215], v[6:9]
	v_mfma_f32_16x16x32_bf16 v[10:13], v[154:157], v[212:215], v[10:13]
	v_mfma_f32_16x16x32_bf16 v[10:13], v[158:161], v[216:219], v[10:13]
	v_mfma_f32_16x16x32_bf16 v[14:17], v[148:151], v[216:219], v[14:17]
	v_mfma_f32_16x16x32_bf16 v[14:17], v[144:147], v[212:215], v[14:17]
	s_setprio 0
	s_barrier
	s_add_i32 s76, s76, 2
	s_add_u32 s62, s62, 0x100
	s_addc_u32 s63, s63, 0
	s_add_u32 s53, s53, 0x100
	s_addc_u32 s58, s58, 0
	s_cmp_gt_u32 s76, 29
	s_cbranch_scc1 .LBB0_584

.LBB0_645:
	s_add_u32 s64, s8, 0x100
	s_addc_u32 s65, s9, 0
	s_and_b64 s[0:1], s[70:71], exec
	s_cselect_b32 s77, s63, s65
	s_cselect_b32 s76, s62, s64
	s_cselect_b32 s71, s85, s23
	s_cselect_b32 s70, s84, s7
	s_add_i32 s0, 0, 0x10000
	s_add_i32 s18, 0, 0x14000
	v_add_u32_e32 v106, s0, v1
	v_add_u32_e32 v154, s18, v1
	ds_read_b128 v[70:73], v106
	ds_read_b128 v[82:85], v106 offset:1024
	ds_read_b128 v[94:97], v106 offset:2048
	ds_read_b128 v[106:109], v106 offset:3072
	ds_read_b128 v[118:121], v154
	ds_read_b128 v[130:133], v154 offset:1024
	ds_read_b128 v[142:145], v154 offset:2048
	ds_read_b128 v[154:157], v154 offset:3072
	s_add_i32 m0, s29, 0xc000
	ds_read_b128 v[158:161], v237
	ds_read_b128 v[170:173], v237 offset:1024
	ds_read_b128 v[174:177], v237 offset:2048
	ds_read_b128 v[178:181], v237 offset:3072
	ds_read_b128 v[182:185], v237 offset:4096
	ds_read_b128 v[186:189], v237 offset:5120
	ds_read_b128 v[210:213], v237 offset:6144
	ds_read_b128 v[214:217], v237 offset:7168
	global_load_lds_dwordx4 v206, s[8:9]
	s_add_i32 m0, s29, 0xe000
	s_nop 0
	global_load_lds_dwordx4 v208, s[8:9]
	s_waitcnt vmcnt(8)
	s_barrier
	s_setprio 1
	s_waitcnt lgkmcnt(0)
	v_mfma_f32_16x16x32_bf16 v[166:169], v[70:73], v[158:161], v[166:169]
	v_mfma_f32_16x16x32_bf16 v[166:169], v[82:85], v[170:173], v[166:169]
	v_mfma_f32_16x16x32_bf16 v[162:165], v[106:109], v[170:173], v[162:165]
	v_mfma_f32_16x16x32_bf16 v[162:165], v[94:97], v[158:161], v[162:165]
	v_mfma_f32_16x16x32_bf16 v[150:153], v[118:121], v[158:161], v[150:153]
	v_mfma_f32_16x16x32_bf16 v[150:153], v[130:133], v[170:173], v[150:153]
	v_mfma_f32_16x16x32_bf16 v[146:149], v[154:157], v[170:173], v[146:149]
	v_mfma_f32_16x16x32_bf16 v[146:149], v[142:145], v[158:161], v[146:149]
	v_mfma_f32_16x16x32_bf16 v[122:125], v[142:145], v[174:177], v[122:125]
	v_mfma_f32_16x16x32_bf16 v[122:125], v[154:157], v[178:181], v[122:125]
	v_mfma_f32_16x16x32_bf16 v[126:129], v[130:133], v[178:181], v[126:129]
	v_mfma_f32_16x16x32_bf16 v[126:129], v[118:121], v[174:177], v[126:129]
	v_mfma_f32_16x16x32_bf16 v[134:137], v[94:97], v[174:177], v[134:137]
	v_mfma_f32_16x16x32_bf16 v[134:137], v[106:109], v[178:181], v[134:137]
	v_mfma_f32_16x16x32_bf16 v[138:141], v[82:85], v[178:181], v[138:141]
	v_mfma_f32_16x16x32_bf16 v[138:141], v[70:73], v[174:177], v[138:141]
	v_mfma_f32_16x16x32_bf16 v[114:117], v[70:73], v[182:185], v[114:117]
	v_mfma_f32_16x16x32_bf16 v[114:117], v[82:85], v[186:189], v[114:117]
	v_mfma_f32_16x16x32_bf16 v[110:113], v[106:109], v[186:189], v[110:113]
	v_mfma_f32_16x16x32_bf16 v[110:113], v[94:97], v[182:185], v[110:113]
	v_mfma_f32_16x16x32_bf16 v[102:105], v[118:121], v[182:185], v[102:105]
	v_mfma_f32_16x16x32_bf16 v[102:105], v[130:133], v[186:189], v[102:105]
	v_mfma_f32_16x16x32_bf16 v[98:101], v[154:157], v[186:189], v[98:101]
	v_mfma_f32_16x16x32_bf16 v[98:101], v[142:145], v[182:185], v[98:101]
	v_mfma_f32_16x16x32_bf16 v[74:77], v[142:145], v[210:213], v[74:77]
	v_mfma_f32_16x16x32_bf16 v[74:77], v[154:157], v[214:217], v[74:77]
	v_mfma_f32_16x16x32_bf16 v[78:81], v[130:133], v[214:217], v[78:81]
	v_mfma_f32_16x16x32_bf16 v[78:81], v[118:121], v[210:213], v[78:81]
	v_mfma_f32_16x16x32_bf16 v[86:89], v[94:97], v[210:213], v[86:89]
	v_mfma_f32_16x16x32_bf16 v[86:89], v[106:109], v[214:217], v[86:89]
	v_mfma_f32_16x16x32_bf16 v[90:93], v[82:85], v[214:217], v[90:93]
	v_mfma_f32_16x16x32_bf16 v[90:93], v[70:73], v[210:213], v[90:93]
	s_setprio 0
	s_barrier
	s_add_i32 s0, s0, s28
	s_mov_b32 m0, s0
	ds_read_b128 v[158:161], v237 offset:16384
	ds_read_b128 v[170:173], v237 offset:17408
	ds_read_b128 v[174:177], v237 offset:18432
	ds_read_b128 v[178:181], v237 offset:19456
	ds_read_b128 v[182:185], v237 offset:20480
	ds_read_b128 v[186:189], v237 offset:21504
	ds_read_b128 v[210:213], v237 offset:22528
	ds_read_b128 v[214:217], v237 offset:23552
	global_load_lds_dwordx4 v192, s[70:71]
	s_add_i32 m0, s0, 0x2000
	s_add_u32 s0, s70, 0x160000
	s_addc_u32 s1, s71, 0
	s_add_i32 s8, s18, s28
	global_load_lds_dwordx4 v190, s[70:71]
	s_mov_b32 m0, s8
	s_nop 0
	global_load_lds_dwordx4 v192, s[0:1]
	s_add_i32 m0, s8, 0x2000
	s_nop 0
	global_load_lds_dwordx4 v190, s[0:1]
	s_mov_b32 m0, s29
	s_nop 0
	global_load_lds_dwordx4 v192, s[76:77]
	s_mov_b32 m0, s31
	s_nop 0
	global_load_lds_dwordx4 v190, s[76:77]
	s_waitcnt vmcnt(8)
	s_barrier
	s_setprio 1
	s_waitcnt lgkmcnt(0)
	v_mfma_f32_16x16x32_bf16 v[62:65], v[70:73], v[158:161], v[62:65]
	v_mfma_f32_16x16x32_bf16 v[62:65], v[82:85], v[170:173], v[62:65]
	v_mfma_f32_16x16x32_bf16 v[58:61], v[106:109], v[170:173], v[58:61]
	v_mfma_f32_16x16x32_bf16 v[58:61], v[94:97], v[158:161], v[58:61]
	v_mfma_f32_16x16x32_bf16 v[54:57], v[118:121], v[158:161], v[54:57]
	v_mfma_f32_16x16x32_bf16 v[54:57], v[130:133], v[170:173], v[54:57]
	v_mfma_f32_16x16x32_bf16 v[50:53], v[154:157], v[170:173], v[50:53]
	v_mfma_f32_16x16x32_bf16 v[50:53], v[142:145], v[158:161], v[50:53]
	v_mfma_f32_16x16x32_bf16 v[34:37], v[142:145], v[174:177], v[34:37]
	v_mfma_f32_16x16x32_bf16 v[34:37], v[154:157], v[178:181], v[34:37]
	v_mfma_f32_16x16x32_bf16 v[38:41], v[130:133], v[178:181], v[38:41]
	v_mfma_f32_16x16x32_bf16 v[38:41], v[118:121], v[174:177], v[38:41]
	v_mfma_f32_16x16x32_bf16 v[42:45], v[94:97], v[174:177], v[42:45]
	v_mfma_f32_16x16x32_bf16 v[42:45], v[106:109], v[178:181], v[42:45]
	v_mfma_f32_16x16x32_bf16 v[46:49], v[82:85], v[178:181], v[46:49]
	v_mfma_f32_16x16x32_bf16 v[46:49], v[70:73], v[174:177], v[46:49]
	v_mfma_f32_16x16x32_bf16 v[30:33], v[70:73], v[182:185], v[30:33]
	v_mfma_f32_16x16x32_bf16 v[30:33], v[82:85], v[186:189], v[30:33]
	v_mfma_f32_16x16x32_bf16 v[26:29], v[106:109], v[186:189], v[26:29]
	v_mfma_f32_16x16x32_bf16 v[26:29], v[94:97], v[182:185], v[26:29]
	v_mfma_f32_16x16x32_bf16 v[22:25], v[118:121], v[182:185], v[22:25]
	v_mfma_f32_16x16x32_bf16 v[22:25], v[130:133], v[186:189], v[22:25]
	v_mfma_f32_16x16x32_bf16 v[18:21], v[154:157], v[186:189], v[18:21]
	v_mfma_f32_16x16x32_bf16 v[18:21], v[142:145], v[182:185], v[18:21]
	v_mfma_f32_16x16x32_bf16 v[2:5], v[142:145], v[210:213], v[2:5]
	v_mfma_f32_16x16x32_bf16 v[2:5], v[154:157], v[214:217], v[2:5]
	v_mfma_f32_16x16x32_bf16 v[6:9], v[130:133], v[214:217], v[6:9]
	v_mfma_f32_16x16x32_bf16 v[6:9], v[118:121], v[210:213], v[6:9]
	v_mfma_f32_16x16x32_bf16 v[10:13], v[94:97], v[210:213], v[10:13]
	v_mfma_f32_16x16x32_bf16 v[10:13], v[106:109], v[214:217], v[10:13]
	v_mfma_f32_16x16x32_bf16 v[14:17], v[82:85], v[214:217], v[14:17]
	v_mfma_f32_16x16x32_bf16 v[14:17], v[70:73], v[210:213], v[14:17]
	s_setprio 0
	s_barrier
	s_add_i32 s8, 0, 0x18000
	s_add_i32 s9, 0, 0x1c000
	v_add_u32_e32 v106, s8, v1
	v_add_u32_e32 v154, s9, v1
	ds_read_b128 v[70:73], v106
	ds_read_b128 v[82:85], v106 offset:1024
	ds_read_b128 v[94:97], v106 offset:2048
	ds_read_b128 v[106:109], v106 offset:3072
	ds_read_b128 v[118:121], v154
	ds_read_b128 v[130:133], v154 offset:1024
	ds_read_b128 v[142:145], v154 offset:2048
	ds_read_b128 v[154:157], v154 offset:3072
	s_add_u32 s0, s76, 0x160000
	s_addc_u32 s1, s77, 0
	s_mov_b32 m0, s33
	ds_read_b128 v[158:161], v237 offset:32768
	ds_read_b128 v[170:173], v237 offset:33792
	ds_read_b128 v[174:177], v237 offset:34816
	ds_read_b128 v[178:181], v237 offset:35840
	ds_read_b128 v[182:185], v237 offset:36864
	ds_read_b128 v[186:189], v237 offset:37888
	ds_read_b128 v[210:213], v237 offset:38912
	ds_read_b128 v[214:217], v237 offset:39936
	global_load_lds_dwordx4 v192, s[0:1]
	s_mov_b32 m0, s43
	s_nop 0
	global_load_lds_dwordx4 v190, s[0:1]
	s_waitcnt vmcnt(8)
	s_barrier
	s_setprio 1
	s_waitcnt lgkmcnt(0)
	v_mfma_f32_16x16x32_bf16 v[166:169], v[70:73], v[158:161], v[166:169]
	v_mfma_f32_16x16x32_bf16 v[166:169], v[82:85], v[170:173], v[166:169]
	v_mfma_f32_16x16x32_bf16 v[162:165], v[106:109], v[170:173], v[162:165]
	v_mfma_f32_16x16x32_bf16 v[162:165], v[94:97], v[158:161], v[162:165]
	v_mfma_f32_16x16x32_bf16 v[150:153], v[118:121], v[158:161], v[150:153]
	v_mfma_f32_16x16x32_bf16 v[150:153], v[130:133], v[170:173], v[150:153]
	v_mfma_f32_16x16x32_bf16 v[146:149], v[154:157], v[170:173], v[146:149]
	v_mfma_f32_16x16x32_bf16 v[146:149], v[142:145], v[158:161], v[146:149]
	v_mfma_f32_16x16x32_bf16 v[122:125], v[142:145], v[174:177], v[122:125]
	v_mfma_f32_16x16x32_bf16 v[122:125], v[154:157], v[178:181], v[122:125]
	v_mfma_f32_16x16x32_bf16 v[126:129], v[130:133], v[178:181], v[126:129]
	v_mfma_f32_16x16x32_bf16 v[126:129], v[118:121], v[174:177], v[126:129]
	v_mfma_f32_16x16x32_bf16 v[134:137], v[94:97], v[174:177], v[134:137]
	v_mfma_f32_16x16x32_bf16 v[134:137], v[106:109], v[178:181], v[134:137]
	v_mfma_f32_16x16x32_bf16 v[138:141], v[82:85], v[178:181], v[138:141]
	v_mfma_f32_16x16x32_bf16 v[138:141], v[70:73], v[174:177], v[138:141]
	v_mfma_f32_16x16x32_bf16 v[114:117], v[70:73], v[182:185], v[114:117]
	v_mfma_f32_16x16x32_bf16 v[114:117], v[82:85], v[186:189], v[114:117]
	v_mfma_f32_16x16x32_bf16 v[110:113], v[106:109], v[186:189], v[110:113]
	v_mfma_f32_16x16x32_bf16 v[110:113], v[94:97], v[182:185], v[110:113]
	v_mfma_f32_16x16x32_bf16 v[102:105], v[118:121], v[182:185], v[102:105]
	v_mfma_f32_16x16x32_bf16 v[102:105], v[130:133], v[186:189], v[102:105]
	v_mfma_f32_16x16x32_bf16 v[98:101], v[154:157], v[186:189], v[98:101]
	v_mfma_f32_16x16x32_bf16 v[98:101], v[142:145], v[182:185], v[98:101]
	v_mfma_f32_16x16x32_bf16 v[74:77], v[142:145], v[210:213], v[74:77]
	v_mfma_f32_16x16x32_bf16 v[74:77], v[154:157], v[214:217], v[74:77]
	v_mfma_f32_16x16x32_bf16 v[78:81], v[130:133], v[214:217], v[78:81]
	v_mfma_f32_16x16x32_bf16 v[78:81], v[118:121], v[210:213], v[78:81]
	v_mfma_f32_16x16x32_bf16 v[86:89], v[94:97], v[210:213], v[86:89]
	v_mfma_f32_16x16x32_bf16 v[86:89], v[106:109], v[214:217], v[86:89]
	v_mfma_f32_16x16x32_bf16 v[90:93], v[82:85], v[214:217], v[90:93]
	v_mfma_f32_16x16x32_bf16 v[90:93], v[70:73], v[210:213], v[90:93]
	s_setprio 0
	s_barrier
	s_add_u32 s98, s70, 0x80
	s_addc_u32 s99, s71, 0
	s_add_u32 s100, s76, 0x80
	s_addc_u32 s101, s77, 0
	s_add_i32 s0, s8, s28
	s_mov_b32 m0, s0
	ds_read_b128 v[158:161], v237 offset:49152
	ds_read_b128 v[170:173], v237 offset:50176
	ds_read_b128 v[174:177], v237 offset:51200
	ds_read_b128 v[178:181], v237 offset:52224
	ds_read_b128 v[182:185], v237 offset:53248
	ds_read_b128 v[186:189], v237 offset:54272
	ds_read_b128 v[210:213], v237 offset:55296
	ds_read_b128 v[214:217], v237 offset:56320
	global_load_lds_dwordx4 v192, s[98:99]
	s_add_i32 m0, s0, 0x2000
	s_add_u32 s0, s70, 0x160080
	s_addc_u32 s1, s71, 0
	s_add_i32 s8, s9, s28
	global_load_lds_dwordx4 v190, s[98:99]
	s_mov_b32 m0, s8
	s_nop 0
	global_load_lds_dwordx4 v192, s[0:1]
	s_add_i32 m0, s8, 0x2000
	s_nop 0
	global_load_lds_dwordx4 v190, s[0:1]
	s_mov_b32 m0, s68
	s_nop 0
	global_load_lds_dwordx4 v192, s[100:101]
	s_mov_b32 m0, s79
	s_nop 0
	global_load_lds_dwordx4 v190, s[100:101]
	s_waitcnt vmcnt(8)
	s_barrier
	s_setprio 1
	s_waitcnt lgkmcnt(0)
	v_mfma_f32_16x16x32_bf16 v[62:65], v[70:73], v[158:161], v[62:65]
	v_mfma_f32_16x16x32_bf16 v[62:65], v[82:85], v[170:173], v[62:65]
	v_mfma_f32_16x16x32_bf16 v[58:61], v[106:109], v[170:173], v[58:61]
	v_mfma_f32_16x16x32_bf16 v[58:61], v[94:97], v[158:161], v[58:61]
	v_mfma_f32_16x16x32_bf16 v[54:57], v[118:121], v[158:161], v[54:57]
	v_mfma_f32_16x16x32_bf16 v[54:57], v[130:133], v[170:173], v[54:57]
	v_mfma_f32_16x16x32_bf16 v[50:53], v[154:157], v[170:173], v[50:53]
	v_mfma_f32_16x16x32_bf16 v[50:53], v[142:145], v[158:161], v[50:53]
	v_mfma_f32_16x16x32_bf16 v[34:37], v[142:145], v[174:177], v[34:37]
	v_mfma_f32_16x16x32_bf16 v[34:37], v[154:157], v[178:181], v[34:37]
	v_mfma_f32_16x16x32_bf16 v[38:41], v[130:133], v[178:181], v[38:41]
	v_mfma_f32_16x16x32_bf16 v[38:41], v[118:121], v[174:177], v[38:41]
	v_mfma_f32_16x16x32_bf16 v[42:45], v[94:97], v[174:177], v[42:45]
	v_mfma_f32_16x16x32_bf16 v[42:45], v[106:109], v[178:181], v[42:45]
	v_mfma_f32_16x16x32_bf16 v[46:49], v[82:85], v[178:181], v[46:49]
	v_mfma_f32_16x16x32_bf16 v[46:49], v[70:73], v[174:177], v[46:49]
	v_mfma_f32_16x16x32_bf16 v[30:33], v[70:73], v[182:185], v[30:33]
	v_mfma_f32_16x16x32_bf16 v[30:33], v[82:85], v[186:189], v[30:33]
	v_mfma_f32_16x16x32_bf16 v[26:29], v[106:109], v[186:189], v[26:29]
	v_mfma_f32_16x16x32_bf16 v[26:29], v[94:97], v[182:185], v[26:29]
	v_mfma_f32_16x16x32_bf16 v[22:25], v[118:121], v[182:185], v[22:25]
	v_mfma_f32_16x16x32_bf16 v[22:25], v[130:133], v[186:189], v[22:25]
	v_mfma_f32_16x16x32_bf16 v[18:21], v[154:157], v[186:189], v[18:21]
	v_mfma_f32_16x16x32_bf16 v[18:21], v[142:145], v[182:185], v[18:21]
	v_mfma_f32_16x16x32_bf16 v[2:5], v[142:145], v[210:213], v[2:5]
	v_mfma_f32_16x16x32_bf16 v[2:5], v[154:157], v[214:217], v[2:5]
	v_mfma_f32_16x16x32_bf16 v[6:9], v[130:133], v[214:217], v[6:9]
	v_mfma_f32_16x16x32_bf16 v[6:9], v[118:121], v[210:213], v[6:9]
	v_mfma_f32_16x16x32_bf16 v[10:13], v[94:97], v[210:213], v[10:13]
	v_mfma_f32_16x16x32_bf16 v[10:13], v[106:109], v[214:217], v[10:13]
	v_mfma_f32_16x16x32_bf16 v[14:17], v[82:85], v[214:217], v[14:17]
	v_mfma_f32_16x16x32_bf16 v[14:17], v[70:73], v[210:213], v[14:17]
	s_setprio 0
	s_barrier
	s_add_i32 s41, s41, 2
	s_add_u32 s7, s7, 0x100
	s_addc_u32 s23, s23, 0
	s_cmpk_gt_u32 s41, 0x55
	s_mov_b64 s[8:9], s[64:65]
	s_cbranch_scc1 .LBB0_648
